# gMLP V rows: 16 coalesced loads per wave staged through the wave's LDS tile (was 16 lane-strided loads, 64 cache lines per instruction)
# speedup vs baseline: 1.0156x; 1.0032x over previous
.LBB0_124:
	s_ashr_i32 s14, s16, 9
	s_ashr_i32 s15, s14, 31
	s_lshl_b64 s[14:15], s[14:15], 12
	s_and_b32 s19, s18, 0xf80
	s_or_b32 s14, s14, s19
	v_mov_b32_e32 v1, s15
	v_or_b32_e32 v0, s14, v156
	s_and_b32 s20, s17, 0x3c0
	v_lshlrev_b64 v[2:3], 7, v[0:1]
	v_lshlrev_b64 v[0:1], 11, v[0:1]
	v_lshl_add_u64 v[0:1], s[28:29], 0, v[0:1]
	s_lshl_b32 s78, s20, 1
	v_lshl_add_u64 v[2:3], s[0:1], 0, v[2:3]
	v_lshl_add_u64 v[28:29], v[0:1], 0, s[78:79]
	s_lshl_b32 s100, s83, 4
	v_lshrrev_b32_e32 v76, 3, v244
	v_add_u32_e32 v76, s100, v76
	s_add_i32 s100, s100, s14
	s_lshl_b32 s100, s100, 7
	s_add_u32 s100, s0, s100
	s_addc_u32 s101, s1, 0
	v_lshlrev_b32_e32 v60, 4, v244
	global_load_dwordx4 v[56:59], v60, s[100:101]
	global_load_dwordx4 v[64:67], v60, s[100:101] offset:1024
	s_lshl_b32 s100, s14, 11
	s_add_u32 s100, s100, s28
	s_addc_u32 s101, s29, 0
	s_add_u32 s100, s100, s78
	s_addc_u32 s101, s101, s79
	s_mul_i32 s32, s83, 0x4400
	v_lshrrev_b32_e32 v105, 3, v244
	v_and_b32_e32 v106, 7, v244
	v_lshlrev_b32_e32 v105, 11, v105
	v_lshl_add_u32 v105, v106, 4, v105
	v_mul_u32_u24_e32 v104, 0x110, v244
	v_add_u32_e32 v104, s32, v104
	v_lshrrev_b32_e32 v107, 4, v244
	v_mul_u32_u24_e32 v107, 0x110, v107
	v_bfe_u32 v108, v244, 3, 1
	v_lshl_add_u32 v107, v108, 7, v107
	v_lshl_add_u32 v107, v106, 4, v107
	v_add_u32_e32 v107, s32, v107
	global_load_dwordx4 v[120:123], v105, s[100:101]
	v_add_u32_e32 v105, 0x4000, v105
	global_load_dwordx4 v[48:51], v105, s[100:101]
	v_add_u32_e32 v105, 0x4000, v105
	global_load_dwordx4 v[40:43], v105, s[100:101]
	v_add_u32_e32 v105, 0x4000, v105
	global_load_dwordx4 v[32:35], v105, s[100:101]
	v_add_u32_e32 v105, 0x4000, v105
	global_load_dwordx4 v[24:27], v105, s[100:101]
	v_add_u32_e32 v105, 0x4000, v105
	global_load_dwordx4 v[16:19], v105, s[100:101]
	v_add_u32_e32 v105, 0x4000, v105
	global_load_dwordx4 v[8:11], v105, s[100:101]
	v_add_u32_e32 v105, 0x4000, v105
	global_load_dwordx4 v[0:3], v105, s[100:101]
	v_add_u32_e32 v105, 0x4000, v105
	global_load_dwordx4 v[124:127], v105, s[100:101]
	v_add_u32_e32 v105, 0x4000, v105
	global_load_dwordx4 v[52:55], v105, s[100:101]
	v_add_u32_e32 v105, 0x4000, v105
	global_load_dwordx4 v[44:47], v105, s[100:101]
	v_add_u32_e32 v105, 0x4000, v105
	global_load_dwordx4 v[36:39], v105, s[100:101]
	v_add_u32_e32 v105, 0x4000, v105
	global_load_dwordx4 v[28:31], v105, s[100:101]
	v_add_u32_e32 v105, 0x4000, v105
	global_load_dwordx4 v[20:23], v105, s[100:101]
	v_add_u32_e32 v105, 0x4000, v105
	global_load_dwordx4 v[12:15], v105, s[100:101]
	v_add_u32_e32 v105, 0x4000, v105
	global_load_dwordx4 v[4:7], v105, s[100:101]
	s_lshl_b32 s22, s20, 2
	s_add_i32 s22, s22, 0
	s_add_i32 s24, s22, 0x22000
	s_add_i32 s22, s22, 0x23000
	s_and_b32 s19, s17, 0x380
	v_add_u32_e32 v175, v165, v169
	v_mov_b32_e32 v155, s15
	v_or_b32_e32 v154, s14, v164
	v_add_u32_e32 v177, v165, v171
	v_mov_b32_e32 v151, s15
	v_or_b32_e32 v150, s14, v166
	v_mov_b32_e32 v147, s15
	v_or_b32_e32 v146, s14, v168
	v_mov_b32_e32 v145, s15
	v_or_b32_e32 v144, s14, v176
	s_add_i32 s16, s16, s26
	s_add_i32 s17, s17, s55
	s_add_i32 s18, s18, s23
	s_cmpk_lt_i32 s16, 0x800
	s_waitcnt vmcnt(16)
	s_nop 0
	v_add_f32_e32 v60, v56, v58
	v_add_f32_e32 v61, v57, v59
	v_add_f32_e32 v68, v64, v66
	v_add_f32_e32 v69, v65, v67
	v_add_f32_dpp v60, v60, v60 quad_perm:[1,0,3,2] row_mask:0xf bank_mask:0xf
	v_add_f32_dpp v61, v61, v61 quad_perm:[1,0,3,2] row_mask:0xf bank_mask:0xf
	v_add_f32_dpp v68, v68, v68 quad_perm:[1,0,3,2] row_mask:0xf bank_mask:0xf
	v_add_f32_dpp v69, v69, v69 quad_perm:[1,0,3,2] row_mask:0xf bank_mask:0xf
	v_add_f32_dpp v60, v60, v60 quad_perm:[2,3,0,1] row_mask:0xf bank_mask:0xf
	v_add_f32_dpp v61, v61, v61 quad_perm:[2,3,0,1] row_mask:0xf bank_mask:0xf
	v_add_f32_dpp v68, v68, v68 quad_perm:[2,3,0,1] row_mask:0xf bank_mask:0xf
	v_add_f32_dpp v69, v69, v69 quad_perm:[2,3,0,1] row_mask:0xf bank_mask:0xf
	v_add_f32_dpp v60, v60, v60 row_half_mirror row_mask:0xf bank_mask:0xf
	v_add_f32_dpp v61, v61, v61 row_half_mirror row_mask:0xf bank_mask:0xf
	v_add_f32_dpp v68, v68, v68 row_half_mirror row_mask:0xf bank_mask:0xf
	v_add_f32_dpp v69, v69, v69 row_half_mirror row_mask:0xf bank_mask:0xf
	s_nop 1
	v_mov_b32_e32 v128, v61
	v_mul_f32_e32 v129, s44, v60
	s_nop 0
	v_mov_b32_e32 v195, v129
	v_pk_mul_f32 v[58:59], v[128:129], v[194:195]
	s_nop 0
	v_sub_f32_e32 v58, v58, v59
	v_max_f32_e32 v58, 0, v58
	v_add_f32_e32 v58, 0x358637bd, v58
	v_cmp_gt_f32_e32 vcc, s61, v58
	v_mul_f32_e32 v59, 0x4f800000, v58
	s_nop 0
	v_cndmask_b32_e32 v58, v58, v59, vcc
	v_sqrt_f32_e32 v59, v58
	s_nop 0
	v_add_u32_e32 v71, -1, v59
	v_fma_f32 v72, -v71, v59, v58
	v_cmp_ge_f32_e64 s[70:71], 0, v72
	v_add_u32_e32 v72, 1, v59
	s_nop 0
	v_cndmask_b32_e64 v71, v59, v71, s[70:71]
	v_fma_f32 v59, -v72, v59, v58
	v_cmp_lt_f32_e64 s[70:71], 0, v59
	s_nop 1
	v_cndmask_b32_e64 v59, v71, v72, s[70:71]
	v_mul_f32_e32 v71, 0x37800000, v59
	v_cndmask_b32_e32 v59, v59, v71, vcc
	v_cmp_class_f32_e32 vcc, v58, v226
	s_nop 1
	v_cndmask_b32_e32 v58, v59, v58, vcc
	v_div_scale_f32 v59, s[70:71], v58, v58, 1.0
	v_rcp_f32_e32 v71, v59
	s_nop 0
	v_fma_f32 v72, -v59, v71, 1.0
	v_fmac_f32_e32 v71, v72, v71
	v_div_scale_f32 v72, vcc, 1.0, v58, 1.0
	v_mul_f32_e32 v73, v72, v71
	v_fma_f32 v74, -v59, v73, v72
	v_fmac_f32_e32 v73, v74, v71
	v_fma_f32 v59, -v59, v73, v72
	v_div_fmas_f32 v59, v59, v71, v73
	v_div_fixup_f32 v59, v59, v58, 1.0
	v_mov_b32_e32 v61, v59
	v_mov_b32_e32 v128, v69
	v_mul_f32_e32 v129, s44, v68
	s_nop 0
	v_mov_b32_e32 v195, v129
	v_pk_mul_f32 v[58:59], v[128:129], v[194:195]
	s_nop 0
	v_sub_f32_e32 v58, v58, v59
	v_max_f32_e32 v58, 0, v58
	v_add_f32_e32 v58, 0x358637bd, v58
	v_cmp_gt_f32_e32 vcc, s61, v58
	v_mul_f32_e32 v59, 0x4f800000, v58
	s_nop 0
	v_cndmask_b32_e32 v58, v58, v59, vcc
	v_sqrt_f32_e32 v59, v58
	s_nop 0
	v_add_u32_e32 v71, -1, v59
	v_fma_f32 v72, -v71, v59, v58
	v_cmp_ge_f32_e64 s[70:71], 0, v72
	v_add_u32_e32 v72, 1, v59
	s_nop 0
	v_cndmask_b32_e64 v71, v59, v71, s[70:71]
	v_fma_f32 v59, -v72, v59, v58
	v_cmp_lt_f32_e64 s[70:71], 0, v59
	s_nop 1
	v_cndmask_b32_e64 v59, v71, v72, s[70:71]
	v_mul_f32_e32 v71, 0x37800000, v59
	v_cndmask_b32_e32 v59, v59, v71, vcc
	v_cmp_class_f32_e32 vcc, v58, v226
	s_nop 1
	v_cndmask_b32_e32 v58, v59, v58, vcc
	v_div_scale_f32 v59, s[70:71], v58, v58, 1.0
	v_rcp_f32_e32 v71, v59
	s_nop 0
	v_fma_f32 v72, -v59, v71, 1.0
	v_fmac_f32_e32 v71, v72, v71
	v_div_scale_f32 v72, vcc, 1.0, v58, 1.0
	v_mul_f32_e32 v73, v72, v71
	v_fma_f32 v74, -v59, v73, v72
	v_fmac_f32_e32 v73, v74, v71
	v_fma_f32 v59, -v59, v73, v72
	v_div_fmas_f32 v59, v59, v71, v73
	v_div_fixup_f32 v59, v59, v58, 1.0
	v_mov_b32_e32 v69, v59
	v_lshrrev_b32_e32 v77, 1, v76
	v_and_b32_e32 v78, 1, v76
	v_mul_u32_u24_e32 v77, 0x110, v77
	v_lshl_add_u32 v77, v78, 3, v77
	ds_write_b64 v77, v[60:61] offset:256
	ds_write_b64 v77, v[68:69] offset:1344
	v_mul_u32_u24_e32 v77, 0x110, v244
	s_waitcnt lgkmcnt(0)
	s_barrier
	ds_read_b128 v[100:103], v77 offset:256
	s_waitcnt lgkmcnt(0)
	v_mov_b32_e32 v56, v100
	v_mov_b32_e32 v58, v101
	v_mov_b32_e32 v57, v102
	v_mov_b32_e32 v59, v103
	v_mov_b32_e32 v60, s24
	v_mov_b32_e32 v61, s22
	s_waitcnt vmcnt(0)
	ds_write_b128 v107, v[120:123] offset:0
	ds_write_b128 v107, v[48:51] offset:1088
	ds_write_b128 v107, v[40:43] offset:2176
	ds_write_b128 v107, v[32:35] offset:3264
	ds_write_b128 v107, v[24:27] offset:4352
	ds_write_b128 v107, v[16:19] offset:5440
	ds_write_b128 v107, v[8:11] offset:6528
	ds_write_b128 v107, v[0:3] offset:7616
	ds_write_b128 v107, v[124:127] offset:8704
	ds_write_b128 v107, v[52:55] offset:9792
	ds_write_b128 v107, v[44:47] offset:10880
	ds_write_b128 v107, v[36:39] offset:11968
	ds_write_b128 v107, v[28:31] offset:13056
	ds_write_b128 v107, v[20:23] offset:14144
	ds_write_b128 v107, v[12:15] offset:15232
	ds_write_b128 v107, v[4:7] offset:16320
	s_waitcnt lgkmcnt(0)
	ds_read_b128 v[120:123], v104 offset:0
	ds_read_b128 v[124:127], v104 offset:128
	ds_read_b128 v[48:51], v104 offset:16
	ds_read_b128 v[52:55], v104 offset:144
	ds_read_b128 v[40:43], v104 offset:32
	ds_read_b128 v[44:47], v104 offset:160
	ds_read_b128 v[32:35], v104 offset:48
	ds_read_b128 v[36:39], v104 offset:176
	ds_read_b128 v[24:27], v104 offset:64
	ds_read_b128 v[28:31], v104 offset:192
	ds_read_b128 v[16:19], v104 offset:80
	ds_read_b128 v[20:23], v104 offset:208
	ds_read_b128 v[8:11], v104 offset:96
	ds_read_b128 v[12:15], v104 offset:224
	ds_read_b128 v[0:3], v104 offset:112
	ds_read_b128 v[4:7], v104 offset:240
	s_waitcnt lgkmcnt(0)
	ds_read_b128 v[62:65], v60
	ds_read_b128 v[66:69], v60 offset:16
	ds_read_b128 v[92:95], v61
	ds_read_b128 v[96:99], v61 offset:16
	v_lshlrev_b32_e32 v79, 16, v52
	v_lshlrev_b32_e32 v78, 16, v48
	v_and_b32_e32 v81, 0xffff0000, v52
	v_and_b32_e32 v80, 0xffff0000, v48
	v_pk_fma_f32 v[78:79], v[56:57], s[44:45], v[78:79] op_sel_hi:[1,0,1] neg_lo:[1,0,0] neg_hi:[1,0,0]
	v_pk_fma_f32 v[80:81], v[56:57], s[44:45], v[80:81] op_sel_hi:[1,0,1] neg_lo:[1,0,0] neg_hi:[1,0,0]
	v_lshlrev_b32_e32 v71, 16, v124
	v_lshlrev_b32_e32 v70, 16, v120
	v_and_b32_e32 v73, 0xffff0000, v124
	v_and_b32_e32 v72, 0xffff0000, v120
	v_pk_fma_f32 v[70:71], v[56:57], s[44:45], v[70:71] op_sel_hi:[1,0,1] neg_lo:[1,0,0] neg_hi:[1,0,0]
	v_pk_fma_f32 v[72:73], v[56:57], s[44:45], v[72:73] op_sel_hi:[1,0,1] neg_lo:[1,0,0] neg_hi:[1,0,0]
	v_pk_mul_f32 v[70:71], v[70:71], v[58:59]
	v_pk_mul_f32 v[72:73], v[72:73], v[58:59]
	s_waitcnt lgkmcnt(1)
	v_pk_fma_f32 v[70:71], v[62:63], v[70:71], v[92:93] op_sel_hi:[0,1,0]
	v_pk_fma_f32 v[62:63], v[62:63], v[72:73], v[92:93] op_sel:[1,0,1]
	v_cvt_pk_bf16_f32 v70, v70, v71
	v_cvt_pk_bf16_f32 v62, v62, v63
	ds_write2_b32 v161, v70, v62 offset1:68
	v_lshlrev_b32_e32 v63, 16, v125
	v_lshlrev_b32_e32 v62, 16, v121
	v_pk_fma_f32 v[62:63], v[56:57], s[44:45], v[62:63] op_sel_hi:[1,0,1] neg_lo:[1,0,0] neg_hi:[1,0,0]
	v_and_b32_e32 v71, 0xffff0000, v125
	v_and_b32_e32 v70, 0xffff0000, v121
	v_pk_mul_f32 v[62:63], v[62:63], v[58:59]
	v_pk_fma_f32 v[70:71], v[56:57], s[44:45], v[70:71] op_sel_hi:[1,0,1] neg_lo:[1,0,0] neg_hi:[1,0,0]
	v_pk_fma_f32 v[62:63], v[64:65], v[62:63], v[94:95] op_sel_hi:[0,1,0]
	v_pk_mul_f32 v[70:71], v[70:71], v[58:59]
	v_mov_b32_e32 v64, v65
	v_mov_b32_e32 v72, v95
	v_pk_fma_f32 v[64:65], v[64:65], v[70:71], v[72:73] op_sel_hi:[0,1,0]
	v_cvt_pk_bf16_f32 v62, v62, v63
	v_cvt_pk_bf16_f32 v63, v64, v65
	ds_write2_b32 v161, v62, v63 offset0:136 offset1:204
	v_lshlrev_b32_e32 v63, 16, v126
	v_lshlrev_b32_e32 v62, 16, v122
	v_and_b32_e32 v65, 0xffff0000, v126
	v_and_b32_e32 v64, 0xffff0000, v122
	v_pk_fma_f32 v[62:63], v[56:57], s[44:45], v[62:63] op_sel_hi:[1,0,1] neg_lo:[1,0,0] neg_hi:[1,0,0]
	v_pk_fma_f32 v[64:65], v[56:57], s[44:45], v[64:65] op_sel_hi:[1,0,1] neg_lo:[1,0,0] neg_hi:[1,0,0]
	v_pk_mul_f32 v[62:63], v[62:63], v[58:59]
	v_pk_mul_f32 v[64:65], v[64:65], v[58:59]
	s_waitcnt lgkmcnt(2)
	v_pk_fma_f32 v[62:63], v[66:67], v[62:63], v[96:97] op_sel_hi:[0,1,0]
	v_pk_fma_f32 v[64:65], v[66:67], v[64:65], v[96:97] op_sel:[1,0,1]
	v_cvt_pk_bf16_f32 v62, v62, v63
	v_cvt_pk_bf16_f32 v63, v64, v65
	v_add_u32_e32 v67, 0x800, v161
	ds_write2_b32 v67, v62, v63 offset0:32 offset1:100
	v_lshlrev_b32_e32 v63, 16, v127
	v_lshlrev_b32_e32 v62, 16, v123
	v_pk_fma_f32 v[62:63], v[56:57], s[44:45], v[62:63] op_sel_hi:[1,0,1] neg_lo:[1,0,0] neg_hi:[1,0,0]
	v_and_b32_e32 v65, 0xffff0000, v127
	v_and_b32_e32 v64, 0xffff0000, v123
	v_pk_mul_f32 v[62:63], v[62:63], v[58:59]
	v_pk_fma_f32 v[64:65], v[56:57], s[44:45], v[64:65] op_sel_hi:[1,0,1] neg_lo:[1,0,0] neg_hi:[1,0,0]
	v_pk_fma_f32 v[62:63], v[68:69], v[62:63], v[98:99] op_sel_hi:[0,1,0]
	v_pk_mul_f32 v[64:65], v[64:65], v[58:59]
	v_mov_b32_e32 v66, v69
	v_mov_b32_e32 v68, v99
	v_pk_fma_f32 v[64:65], v[66:67], v[64:65], v[68:69] op_sel_hi:[0,1,0]
	v_cvt_pk_bf16_f32 v62, v62, v63
	v_cvt_pk_bf16_f32 v63, v64, v65
	ds_write2_b32 v67, v62, v63 offset0:168 offset1:236
	ds_read_b128 v[62:65], v60 offset:32
	ds_read_b128 v[66:69], v60 offset:48
	ds_read_b128 v[70:73], v61 offset:32
	ds_read_b128 v[74:77], v61 offset:48
	v_pk_mul_f32 v[78:79], v[78:79], v[58:59]
	v_pk_mul_f32 v[80:81], v[80:81], v[58:59]
	s_waitcnt lgkmcnt(1)
	v_pk_fma_f32 v[78:79], v[62:63], v[78:79], v[70:71] op_sel_hi:[0,1,0]
	v_pk_fma_f32 v[62:63], v[62:63], v[80:81], v[70:71] op_sel:[1,0,1]
	v_cvt_pk_bf16_f32 v48, v78, v79
	v_cvt_pk_bf16_f32 v52, v62, v63
	v_add_u32_e32 v62, 0x1000, v161
	ds_write2_b32 v62, v48, v52 offset0:64 offset1:132
	v_lshlrev_b32_e32 v63, 16, v53
	v_lshlrev_b32_e32 v62, 16, v49
	v_pk_fma_f32 v[62:63], v[56:57], s[44:45], v[62:63] op_sel_hi:[1,0,1] neg_lo:[1,0,0] neg_hi:[1,0,0]
	v_and_b32_e32 v53, 0xffff0000, v53
	v_and_b32_e32 v52, 0xffff0000, v49
	v_pk_mul_f32 v[62:63], v[62:63], v[58:59]
	v_pk_fma_f32 v[48:49], v[56:57], s[44:45], v[52:53] op_sel_hi:[1,0,1] neg_lo:[1,0,0] neg_hi:[1,0,0]
	v_pk_fma_f32 v[62:63], v[64:65], v[62:63], v[72:73] op_sel_hi:[0,1,0]
	v_pk_mul_f32 v[48:49], v[48:49], v[58:59]
	v_mov_b32_e32 v52, v65
	v_mov_b32_e32 v64, v73
	v_pk_fma_f32 v[48:49], v[52:53], v[48:49], v[64:65] op_sel_hi:[0,1,0]
	v_cvt_pk_bf16_f32 v52, v62, v63
	v_cvt_pk_bf16_f32 v48, v48, v49
	v_add_u32_e32 v49, 0x1200, v161
	ds_write2_b32 v49, v52, v48 offset0:72 offset1:140
	v_lshlrev_b32_e32 v49, 16, v54
	v_lshlrev_b32_e32 v48, 16, v50
	v_and_b32_e32 v53, 0xffff0000, v54
	v_and_b32_e32 v52, 0xffff0000, v50
	v_pk_fma_f32 v[48:49], v[56:57], s[44:45], v[48:49] op_sel_hi:[1,0,1] neg_lo:[1,0,0] neg_hi:[1,0,0]
	v_pk_fma_f32 v[52:53], v[56:57], s[44:45], v[52:53] op_sel_hi:[1,0,1] neg_lo:[1,0,0] neg_hi:[1,0,0]
	v_pk_mul_f32 v[48:49], v[48:49], v[58:59]
	v_pk_mul_f32 v[52:53], v[52:53], v[58:59]
	s_waitcnt lgkmcnt(2)
	v_pk_fma_f32 v[48:49], v[66:67], v[48:49], v[74:75] op_sel_hi:[0,1,0]
	v_pk_fma_f32 v[52:53], v[66:67], v[52:53], v[74:75] op_sel:[1,0,1]
	v_cvt_pk_bf16_f32 v48, v48, v49
	v_cvt_pk_bf16_f32 v49, v52, v53
	v_add_u32_e32 v50, 0x1800, v161
	ds_write2_b32 v50, v48, v49 offset0:96 offset1:164
	v_lshlrev_b32_e32 v49, 16, v55
	v_lshlrev_b32_e32 v48, 16, v51
	v_and_b32_e32 v53, 0xffff0000, v55
	v_and_b32_e32 v52, 0xffff0000, v51
	v_pk_fma_f32 v[48:49], v[56:57], s[44:45], v[48:49] op_sel_hi:[1,0,1] neg_lo:[1,0,0] neg_hi:[1,0,0]
	v_pk_fma_f32 v[50:51], v[56:57], s[44:45], v[52:53] op_sel_hi:[1,0,1] neg_lo:[1,0,0] neg_hi:[1,0,0]
	v_pk_mul_f32 v[48:49], v[48:49], v[58:59]
	v_pk_mul_f32 v[50:51], v[50:51], v[58:59]
	v_mov_b32_e32 v52, v69
	v_mov_b32_e32 v54, v77
	v_pk_fma_f32 v[48:49], v[68:69], v[48:49], v[76:77] op_sel_hi:[0,1,0]
	v_pk_fma_f32 v[50:51], v[52:53], v[50:51], v[54:55] op_sel_hi:[0,1,0]
	v_cvt_pk_bf16_f32 v48, v48, v49
	v_cvt_pk_bf16_f32 v49, v50, v51
	v_add_u32_e32 v50, 0x1a00, v161
	ds_write2_b32 v50, v48, v49 offset0:104 offset1:172
	ds_read_b128 v[48:51], v60 offset:64
	ds_read_b128 v[52:55], v60 offset:80
	ds_read_b128 v[62:65], v61 offset:64
	ds_read_b128 v[66:69], v61 offset:80
	v_lshlrev_b32_e32 v71, 16, v44
	v_lshlrev_b32_e32 v70, 16, v40
	v_and_b32_e32 v73, 0xffff0000, v44
	v_and_b32_e32 v72, 0xffff0000, v40
	v_pk_fma_f32 v[70:71], v[56:57], s[44:45], v[70:71] op_sel_hi:[1,0,1] neg_lo:[1,0,0] neg_hi:[1,0,0]
	v_pk_fma_f32 v[72:73], v[56:57], s[44:45], v[72:73] op_sel_hi:[1,0,1] neg_lo:[1,0,0] neg_hi:[1,0,0]
	v_pk_mul_f32 v[70:71], v[70:71], v[58:59]
	v_pk_mul_f32 v[72:73], v[72:73], v[58:59]
	s_waitcnt lgkmcnt(1)
	v_pk_fma_f32 v[70:71], v[70:71], v[48:49], v[62:63] op_sel_hi:[1,0,0]
	v_pk_fma_f32 v[48:49], v[72:73], v[48:49], v[62:63] op_sel:[0,1,1]
	v_cvt_pk_bf16_f32 v40, v70, v71
	v_cvt_pk_bf16_f32 v44, v48, v49
	v_add_u32_e32 v62, 0x400, v161
	v_lshlrev_b32_e32 v49, 16, v45
	v_lshlrev_b32_e32 v48, 16, v41
	ds_write2_b32 v62, v40, v44 offset0:16 offset1:84
	v_pk_fma_f32 v[48:49], v[56:57], s[44:45], v[48:49] op_sel_hi:[1,0,1] neg_lo:[1,0,0] neg_hi:[1,0,0]
	v_and_b32_e32 v45, 0xffff0000, v45
	v_and_b32_e32 v44, 0xffff0000, v41
	v_pk_mul_f32 v[48:49], v[48:49], v[58:59]
	v_pk_fma_f32 v[40:41], v[56:57], s[44:45], v[44:45] op_sel_hi:[1,0,1] neg_lo:[1,0,0] neg_hi:[1,0,0]
	v_pk_fma_f32 v[48:49], v[48:49], v[50:51], v[64:65] op_sel_hi:[1,0,0]
	v_pk_mul_f32 v[40:41], v[40:41], v[58:59]
	v_mov_b32_e32 v44, v51
	v_mov_b32_e32 v50, v65
	v_pk_fma_f32 v[40:41], v[40:41], v[44:45], v[50:51] op_sel_hi:[1,0,0]
	v_cvt_pk_bf16_f32 v44, v48, v49
	v_cvt_pk_bf16_f32 v40, v40, v41
	ds_write2_b32 v62, v44, v40 offset0:152 offset1:220
	v_lshlrev_b32_e32 v41, 16, v46
	v_lshlrev_b32_e32 v40, 16, v42
	v_and_b32_e32 v45, 0xffff0000, v46
	v_and_b32_e32 v44, 0xffff0000, v42
	v_pk_fma_f32 v[40:41], v[56:57], s[44:45], v[40:41] op_sel_hi:[1,0,1] neg_lo:[1,0,0] neg_hi:[1,0,0]
	v_pk_fma_f32 v[44:45], v[56:57], s[44:45], v[44:45] op_sel_hi:[1,0,1] neg_lo:[1,0,0] neg_hi:[1,0,0]
	v_pk_mul_f32 v[40:41], v[40:41], v[58:59]
	v_pk_mul_f32 v[44:45], v[44:45], v[58:59]
	s_waitcnt lgkmcnt(2)
	v_pk_fma_f32 v[40:41], v[40:41], v[52:53], v[66:67] op_sel_hi:[1,0,0]
	v_pk_fma_f32 v[44:45], v[44:45], v[52:53], v[66:67] op_sel:[0,1,1]
	v_cvt_pk_bf16_f32 v40, v40, v41
	v_cvt_pk_bf16_f32 v41, v44, v45
	v_add_u32_e32 v48, 0xc00, v161
	ds_write2_b32 v48, v40, v41 offset0:48 offset1:116
	v_lshlrev_b32_e32 v41, 16, v47
	v_lshlrev_b32_e32 v40, 16, v43
	v_and_b32_e32 v45, 0xffff0000, v47
	v_and_b32_e32 v44, 0xffff0000, v43
	v_pk_fma_f32 v[40:41], v[56:57], s[44:45], v[40:41] op_sel_hi:[1,0,1] neg_lo:[1,0,0] neg_hi:[1,0,0]
	v_pk_fma_f32 v[42:43], v[56:57], s[44:45], v[44:45] op_sel_hi:[1,0,1] neg_lo:[1,0,0] neg_hi:[1,0,0]
	v_pk_mul_f32 v[40:41], v[40:41], v[58:59]
	v_pk_mul_f32 v[42:43], v[42:43], v[58:59]
	v_mov_b32_e32 v44, v55
	v_mov_b32_e32 v46, v69
	v_pk_fma_f32 v[40:41], v[40:41], v[54:55], v[68:69] op_sel_hi:[1,0,0]
	v_pk_fma_f32 v[42:43], v[42:43], v[44:45], v[46:47] op_sel_hi:[1,0,0]
	v_cvt_pk_bf16_f32 v40, v40, v41
	v_cvt_pk_bf16_f32 v41, v42, v43
	ds_write2_b32 v48, v40, v41 offset0:184 offset1:252
	ds_read_b128 v[40:43], v60 offset:96
	ds_read_b128 v[44:47], v60 offset:112
	ds_read_b128 v[48:51], v61 offset:96
	ds_read_b128 v[52:55], v61 offset:112
	v_lshlrev_b32_e32 v63, 16, v36
	v_lshlrev_b32_e32 v62, 16, v32
	v_and_b32_e32 v65, 0xffff0000, v36
	v_and_b32_e32 v64, 0xffff0000, v32
	v_pk_fma_f32 v[62:63], v[56:57], s[44:45], v[62:63] op_sel_hi:[1,0,1] neg_lo:[1,0,0] neg_hi:[1,0,0]
	v_pk_fma_f32 v[64:65], v[56:57], s[44:45], v[64:65] op_sel_hi:[1,0,1] neg_lo:[1,0,0] neg_hi:[1,0,0]
	v_pk_mul_f32 v[62:63], v[62:63], v[58:59]
	v_pk_mul_f32 v[64:65], v[64:65], v[58:59]
	s_waitcnt lgkmcnt(1)
	v_pk_fma_f32 v[62:63], v[62:63], v[40:41], v[48:49] op_sel_hi:[1,0,0]
	v_pk_fma_f32 v[40:41], v[64:65], v[40:41], v[48:49] op_sel:[0,1,1]
	v_cvt_pk_bf16_f32 v32, v62, v63
	v_cvt_pk_bf16_f32 v36, v40, v41
	v_add_u32_e32 v40, 0x1400, v161
	ds_write2_b32 v40, v32, v36 offset0:80 offset1:148
	v_lshlrev_b32_e32 v41, 16, v37
	v_lshlrev_b32_e32 v40, 16, v33
	v_pk_fma_f32 v[40:41], v[56:57], s[44:45], v[40:41] op_sel_hi:[1,0,1] neg_lo:[1,0,0] neg_hi:[1,0,0]
	v_and_b32_e32 v37, 0xffff0000, v37
	v_and_b32_e32 v36, 0xffff0000, v33
	v_pk_mul_f32 v[40:41], v[40:41], v[58:59]
	v_pk_fma_f32 v[32:33], v[56:57], s[44:45], v[36:37] op_sel_hi:[1,0,1] neg_lo:[1,0,0] neg_hi:[1,0,0]
	v_pk_fma_f32 v[40:41], v[40:41], v[42:43], v[50:51] op_sel_hi:[1,0,0]
	v_pk_mul_f32 v[32:33], v[32:33], v[58:59]
	v_mov_b32_e32 v36, v43
	v_mov_b32_e32 v42, v51
	v_pk_fma_f32 v[32:33], v[32:33], v[36:37], v[42:43] op_sel_hi:[1,0,0]
	v_cvt_pk_bf16_f32 v36, v40, v41
	v_cvt_pk_bf16_f32 v32, v32, v33
	v_add_u32_e32 v33, 0x1600, v161
	ds_write2_b32 v33, v36, v32 offset0:88 offset1:156
	v_lshlrev_b32_e32 v33, 16, v38
	v_lshlrev_b32_e32 v32, 16, v34
	v_and_b32_e32 v37, 0xffff0000, v38
	v_and_b32_e32 v36, 0xffff0000, v34
	v_pk_fma_f32 v[32:33], v[56:57], s[44:45], v[32:33] op_sel_hi:[1,0,1] neg_lo:[1,0,0] neg_hi:[1,0,0]
	v_pk_fma_f32 v[36:37], v[56:57], s[44:45], v[36:37] op_sel_hi:[1,0,1] neg_lo:[1,0,0] neg_hi:[1,0,0]
	v_pk_mul_f32 v[32:33], v[32:33], v[58:59]
	v_pk_mul_f32 v[36:37], v[36:37], v[58:59]
	s_waitcnt lgkmcnt(2)
	v_pk_fma_f32 v[32:33], v[32:33], v[44:45], v[52:53] op_sel_hi:[1,0,0]
	v_pk_fma_f32 v[36:37], v[36:37], v[44:45], v[52:53] op_sel:[0,1,1]
	v_cvt_pk_bf16_f32 v32, v32, v33
	v_cvt_pk_bf16_f32 v33, v36, v37
	v_add_u32_e32 v34, 0x1c00, v161
	ds_write2_b32 v34, v32, v33 offset0:112 offset1:180
	v_lshlrev_b32_e32 v33, 16, v39
	v_lshlrev_b32_e32 v32, 16, v35
	v_and_b32_e32 v37, 0xffff0000, v39
	v_and_b32_e32 v36, 0xffff0000, v35
	v_pk_fma_f32 v[32:33], v[56:57], s[44:45], v[32:33] op_sel_hi:[1,0,1] neg_lo:[1,0,0] neg_hi:[1,0,0]
	v_pk_fma_f32 v[34:35], v[56:57], s[44:45], v[36:37] op_sel_hi:[1,0,1] neg_lo:[1,0,0] neg_hi:[1,0,0]
	v_pk_mul_f32 v[32:33], v[32:33], v[58:59]
	v_pk_mul_f32 v[34:35], v[34:35], v[58:59]
	v_mov_b32_e32 v36, v47
	v_mov_b32_e32 v38, v55
	v_pk_fma_f32 v[32:33], v[32:33], v[46:47], v[54:55] op_sel_hi:[1,0,0]
	v_pk_fma_f32 v[34:35], v[34:35], v[36:37], v[38:39] op_sel_hi:[1,0,0]
	v_cvt_pk_bf16_f32 v32, v32, v33
	v_cvt_pk_bf16_f32 v33, v34, v35
	v_add_u32_e32 v34, 0x1e00, v161
	ds_write2_b32 v34, v32, v33 offset0:120 offset1:188
	ds_read_b128 v[32:35], v60 offset:128
	ds_read_b128 v[36:39], v60 offset:144
	ds_read_b128 v[40:43], v61 offset:128
	ds_read_b128 v[44:47], v61 offset:144
	v_lshlrev_b32_e32 v49, 16, v28
	v_lshlrev_b32_e32 v48, 16, v24
	v_and_b32_e32 v51, 0xffff0000, v28
	v_and_b32_e32 v50, 0xffff0000, v24
	v_pk_fma_f32 v[48:49], v[56:57], s[44:45], v[48:49] op_sel_hi:[1,0,1] neg_lo:[1,0,0] neg_hi:[1,0,0]
	v_pk_fma_f32 v[50:51], v[56:57], s[44:45], v[50:51] op_sel_hi:[1,0,1] neg_lo:[1,0,0] neg_hi:[1,0,0]
	v_pk_mul_f32 v[48:49], v[48:49], v[58:59]
	v_pk_mul_f32 v[50:51], v[50:51], v[58:59]
	s_waitcnt lgkmcnt(1)
	v_pk_fma_f32 v[48:49], v[48:49], v[32:33], v[40:41] op_sel_hi:[1,0,0]
	v_pk_fma_f32 v[32:33], v[50:51], v[32:33], v[40:41] op_sel:[0,1,1]
	v_cvt_pk_bf16_f32 v24, v48, v49
	v_cvt_pk_bf16_f32 v28, v32, v33
	v_add_u32_e32 v32, 0x2000, v161
	ds_write2_b32 v32, v24, v28 offset0:128 offset1:196
	v_lshlrev_b32_e32 v33, 16, v29
	v_lshlrev_b32_e32 v32, 16, v25
	v_pk_fma_f32 v[32:33], v[56:57], s[44:45], v[32:33] op_sel_hi:[1,0,1] neg_lo:[1,0,0] neg_hi:[1,0,0]
	v_and_b32_e32 v29, 0xffff0000, v29
	v_and_b32_e32 v28, 0xffff0000, v25
	v_pk_mul_f32 v[32:33], v[32:33], v[58:59]
	v_pk_fma_f32 v[24:25], v[56:57], s[44:45], v[28:29] op_sel_hi:[1,0,1] neg_lo:[1,0,0] neg_hi:[1,0,0]
	v_pk_fma_f32 v[32:33], v[32:33], v[34:35], v[42:43] op_sel_hi:[1,0,0]
	v_pk_mul_f32 v[24:25], v[24:25], v[58:59]
	v_mov_b32_e32 v28, v35
	v_mov_b32_e32 v34, v43
	v_pk_fma_f32 v[24:25], v[24:25], v[28:29], v[34:35] op_sel_hi:[1,0,0]
	v_cvt_pk_bf16_f32 v28, v32, v33
	v_cvt_pk_bf16_f32 v24, v24, v25
	v_add_u32_e32 v48, 0x2400, v161
	ds_write2_b32 v48, v28, v24 offset0:8 offset1:76
	v_lshlrev_b32_e32 v25, 16, v30
	v_lshlrev_b32_e32 v24, 16, v26
	v_and_b32_e32 v29, 0xffff0000, v30
	v_and_b32_e32 v28, 0xffff0000, v26
	v_pk_fma_f32 v[24:25], v[56:57], s[44:45], v[24:25] op_sel_hi:[1,0,1] neg_lo:[1,0,0] neg_hi:[1,0,0]
	v_pk_fma_f32 v[28:29], v[56:57], s[44:45], v[28:29] op_sel_hi:[1,0,1] neg_lo:[1,0,0] neg_hi:[1,0,0]
	v_pk_mul_f32 v[24:25], v[24:25], v[58:59]
	v_pk_mul_f32 v[28:29], v[28:29], v[58:59]
	s_waitcnt lgkmcnt(2)
	v_pk_fma_f32 v[24:25], v[24:25], v[36:37], v[44:45] op_sel_hi:[1,0,0]
	v_pk_fma_f32 v[28:29], v[28:29], v[36:37], v[44:45] op_sel:[0,1,1]
	v_cvt_pk_bf16_f32 v24, v24, v25
	v_cvt_pk_bf16_f32 v25, v28, v29
	v_add_u32_e32 v44, 0x2800, v161
	ds_write2_b32 v44, v24, v25 offset0:160 offset1:228
	v_lshlrev_b32_e32 v25, 16, v31
	v_lshlrev_b32_e32 v24, 16, v27
	v_and_b32_e32 v29, 0xffff0000, v31
	v_and_b32_e32 v28, 0xffff0000, v27
	v_pk_fma_f32 v[24:25], v[56:57], s[44:45], v[24:25] op_sel_hi:[1,0,1] neg_lo:[1,0,0] neg_hi:[1,0,0]
	v_pk_fma_f32 v[26:27], v[56:57], s[44:45], v[28:29] op_sel_hi:[1,0,1] neg_lo:[1,0,0] neg_hi:[1,0,0]
	v_pk_mul_f32 v[24:25], v[24:25], v[58:59]
	v_pk_mul_f32 v[26:27], v[26:27], v[58:59]
	v_mov_b32_e32 v28, v39
	v_mov_b32_e32 v30, v47
	v_pk_fma_f32 v[24:25], v[24:25], v[38:39], v[46:47] op_sel_hi:[1,0,0]
	v_pk_fma_f32 v[26:27], v[26:27], v[28:29], v[30:31] op_sel_hi:[1,0,0]
	v_cvt_pk_bf16_f32 v24, v24, v25
	v_cvt_pk_bf16_f32 v25, v26, v27
	v_add_u32_e32 v45, 0x2c00, v161
	ds_write2_b32 v45, v24, v25 offset0:40 offset1:108
	ds_read_b128 v[24:27], v60 offset:160
	ds_read_b128 v[28:31], v60 offset:176
	ds_read_b128 v[32:35], v61 offset:160
	ds_read_b128 v[36:39], v61 offset:176
	v_lshlrev_b32_e32 v41, 16, v20
	v_lshlrev_b32_e32 v40, 16, v16
	v_and_b32_e32 v43, 0xffff0000, v20
	v_and_b32_e32 v42, 0xffff0000, v16
	v_pk_fma_f32 v[40:41], v[56:57], s[44:45], v[40:41] op_sel_hi:[1,0,1] neg_lo:[1,0,0] neg_hi:[1,0,0]
	v_pk_fma_f32 v[42:43], v[56:57], s[44:45], v[42:43] op_sel_hi:[1,0,1] neg_lo:[1,0,0] neg_hi:[1,0,0]
	v_pk_mul_f32 v[40:41], v[40:41], v[58:59]
	v_pk_mul_f32 v[42:43], v[42:43], v[58:59]
	s_waitcnt lgkmcnt(1)
	v_pk_fma_f32 v[40:41], v[40:41], v[24:25], v[32:33] op_sel_hi:[1,0,0]
	v_pk_fma_f32 v[24:25], v[42:43], v[24:25], v[32:33] op_sel:[0,1,1]
	v_cvt_pk_bf16_f32 v16, v40, v41
	v_cvt_pk_bf16_f32 v20, v24, v25
	v_add_u32_e32 v24, 0x3200, v161
	ds_write2_b32 v24, v16, v20 offset0:64 offset1:132
	v_lshlrev_b32_e32 v25, 16, v21
	v_lshlrev_b32_e32 v24, 16, v17
	v_pk_fma_f32 v[24:25], v[56:57], s[44:45], v[24:25] op_sel_hi:[1,0,1] neg_lo:[1,0,0] neg_hi:[1,0,0]
	v_and_b32_e32 v21, 0xffff0000, v21
	v_and_b32_e32 v20, 0xffff0000, v17
	v_pk_mul_f32 v[24:25], v[24:25], v[58:59]
	v_pk_fma_f32 v[16:17], v[56:57], s[44:45], v[20:21] op_sel_hi:[1,0,1] neg_lo:[1,0,0] neg_hi:[1,0,0]
	v_pk_fma_f32 v[24:25], v[24:25], v[26:27], v[34:35] op_sel_hi:[1,0,0]
	v_pk_mul_f32 v[16:17], v[16:17], v[58:59]
	v_mov_b32_e32 v20, v27
	v_mov_b32_e32 v26, v35
	v_pk_fma_f32 v[16:17], v[16:17], v[20:21], v[26:27] op_sel_hi:[1,0,0]
	v_cvt_pk_bf16_f32 v20, v24, v25
	v_cvt_pk_bf16_f32 v16, v16, v17
	v_add_u32_e32 v17, 0x3400, v161
	ds_write2_b32 v17, v20, v16 offset0:72 offset1:140
	v_lshlrev_b32_e32 v17, 16, v22
	v_lshlrev_b32_e32 v16, 16, v18
	v_and_b32_e32 v21, 0xffff0000, v22
	v_and_b32_e32 v20, 0xffff0000, v18
	v_pk_fma_f32 v[16:17], v[56:57], s[44:45], v[16:17] op_sel_hi:[1,0,1] neg_lo:[1,0,0] neg_hi:[1,0,0]
	v_pk_fma_f32 v[20:21], v[56:57], s[44:45], v[20:21] op_sel_hi:[1,0,1] neg_lo:[1,0,0] neg_hi:[1,0,0]
	v_pk_mul_f32 v[16:17], v[16:17], v[58:59]
	v_pk_mul_f32 v[20:21], v[20:21], v[58:59]
	s_waitcnt lgkmcnt(2)
	v_pk_fma_f32 v[16:17], v[16:17], v[28:29], v[36:37] op_sel_hi:[1,0,0]
	v_pk_fma_f32 v[20:21], v[20:21], v[28:29], v[36:37] op_sel:[0,1,1]
	v_cvt_pk_bf16_f32 v16, v16, v17
	v_cvt_pk_bf16_f32 v17, v20, v21
	v_add_u32_e32 v18, 0x3a00, v161
	ds_write2_b32 v18, v16, v17 offset0:96 offset1:164
	v_lshlrev_b32_e32 v17, 16, v23
	v_lshlrev_b32_e32 v16, 16, v19
	v_and_b32_e32 v21, 0xffff0000, v23
	v_and_b32_e32 v20, 0xffff0000, v19
	v_pk_fma_f32 v[16:17], v[56:57], s[44:45], v[16:17] op_sel_hi:[1,0,1] neg_lo:[1,0,0] neg_hi:[1,0,0]
	v_pk_fma_f32 v[18:19], v[56:57], s[44:45], v[20:21] op_sel_hi:[1,0,1] neg_lo:[1,0,0] neg_hi:[1,0,0]
	v_pk_mul_f32 v[16:17], v[16:17], v[58:59]
	v_pk_mul_f32 v[18:19], v[18:19], v[58:59]
	v_mov_b32_e32 v20, v31
	v_mov_b32_e32 v22, v39
	v_pk_fma_f32 v[16:17], v[16:17], v[30:31], v[38:39] op_sel_hi:[1,0,0]
	v_pk_fma_f32 v[18:19], v[18:19], v[20:21], v[22:23] op_sel_hi:[1,0,0]
	v_cvt_pk_bf16_f32 v16, v16, v17
	v_cvt_pk_bf16_f32 v17, v18, v19
	v_add_u32_e32 v18, 0x3c00, v161
	ds_write2_b32 v18, v16, v17 offset0:104 offset1:172
	ds_read_b128 v[16:19], v60 offset:192
	ds_read_b128 v[20:23], v60 offset:208
	ds_read_b128 v[24:27], v61 offset:192
	ds_read_b128 v[28:31], v61 offset:208
	v_lshlrev_b32_e32 v33, 16, v12
	v_lshlrev_b32_e32 v32, 16, v8
	v_and_b32_e32 v35, 0xffff0000, v12
	v_and_b32_e32 v34, 0xffff0000, v8
	v_pk_fma_f32 v[32:33], v[56:57], s[44:45], v[32:33] op_sel_hi:[1,0,1] neg_lo:[1,0,0] neg_hi:[1,0,0]
	v_pk_fma_f32 v[34:35], v[56:57], s[44:45], v[34:35] op_sel_hi:[1,0,1] neg_lo:[1,0,0] neg_hi:[1,0,0]
	v_pk_mul_f32 v[32:33], v[32:33], v[58:59]
	v_pk_mul_f32 v[34:35], v[34:35], v[58:59]
	s_waitcnt lgkmcnt(1)
	v_pk_fma_f32 v[32:33], v[32:33], v[16:17], v[24:25] op_sel_hi:[1,0,0]
	v_pk_fma_f32 v[16:17], v[34:35], v[16:17], v[24:25] op_sel:[0,1,1]
	v_cvt_pk_bf16_f32 v8, v32, v33
	v_cvt_pk_bf16_f32 v12, v16, v17
	v_lshlrev_b32_e32 v17, 16, v13
	v_lshlrev_b32_e32 v16, 16, v9
	ds_write2_b32 v48, v8, v12 offset0:144 offset1:212
	v_pk_fma_f32 v[16:17], v[56:57], s[44:45], v[16:17] op_sel_hi:[1,0,1] neg_lo:[1,0,0] neg_hi:[1,0,0]
	v_and_b32_e32 v13, 0xffff0000, v13
	v_and_b32_e32 v12, 0xffff0000, v9
	v_pk_mul_f32 v[16:17], v[16:17], v[58:59]
	v_pk_fma_f32 v[8:9], v[56:57], s[44:45], v[12:13] op_sel_hi:[1,0,1] neg_lo:[1,0,0] neg_hi:[1,0,0]
	v_pk_fma_f32 v[16:17], v[16:17], v[18:19], v[26:27] op_sel_hi:[1,0,0]
	v_pk_mul_f32 v[8:9], v[8:9], v[58:59]
	v_mov_b32_e32 v12, v19
	v_mov_b32_e32 v18, v27
	v_pk_fma_f32 v[8:9], v[8:9], v[12:13], v[18:19] op_sel_hi:[1,0,0]
	v_cvt_pk_bf16_f32 v12, v16, v17
	v_cvt_pk_bf16_f32 v8, v8, v9
	ds_write2_b32 v44, v12, v8 offset0:24 offset1:92
	v_lshlrev_b32_e32 v9, 16, v14
	v_lshlrev_b32_e32 v8, 16, v10
	v_and_b32_e32 v13, 0xffff0000, v14
	v_and_b32_e32 v12, 0xffff0000, v10
	v_pk_fma_f32 v[8:9], v[56:57], s[44:45], v[8:9] op_sel_hi:[1,0,1] neg_lo:[1,0,0] neg_hi:[1,0,0]
	v_pk_fma_f32 v[12:13], v[56:57], s[44:45], v[12:13] op_sel_hi:[1,0,1] neg_lo:[1,0,0] neg_hi:[1,0,0]
	v_pk_mul_f32 v[8:9], v[8:9], v[58:59]
	v_pk_mul_f32 v[12:13], v[12:13], v[58:59]
	s_waitcnt lgkmcnt(2)
	v_pk_fma_f32 v[8:9], v[8:9], v[20:21], v[28:29] op_sel_hi:[1,0,0]
	v_pk_fma_f32 v[12:13], v[12:13], v[20:21], v[28:29] op_sel:[0,1,1]
	v_cvt_pk_bf16_f32 v8, v8, v9
	v_cvt_pk_bf16_f32 v9, v12, v13
	ds_write2_b32 v45, v8, v9 offset0:176 offset1:244
	v_lshlrev_b32_e32 v9, 16, v15
	v_lshlrev_b32_e32 v8, 16, v11
	v_and_b32_e32 v13, 0xffff0000, v15
	v_and_b32_e32 v12, 0xffff0000, v11
	v_pk_fma_f32 v[8:9], v[56:57], s[44:45], v[8:9] op_sel_hi:[1,0,1] neg_lo:[1,0,0] neg_hi:[1,0,0]
	v_pk_fma_f32 v[10:11], v[56:57], s[44:45], v[12:13] op_sel_hi:[1,0,1] neg_lo:[1,0,0] neg_hi:[1,0,0]
	v_pk_mul_f32 v[8:9], v[8:9], v[58:59]
	v_pk_mul_f32 v[10:11], v[10:11], v[58:59]
	v_mov_b32_e32 v12, v23
	v_mov_b32_e32 v14, v31
	v_pk_fma_f32 v[8:9], v[8:9], v[22:23], v[30:31] op_sel_hi:[1,0,0]
	v_pk_fma_f32 v[10:11], v[10:11], v[12:13], v[14:15] op_sel_hi:[1,0,0]
	v_cvt_pk_bf16_f32 v8, v8, v9
	v_cvt_pk_bf16_f32 v9, v10, v11
	v_add_u32_e32 v10, 0x3000, v161
	ds_write2_b32 v10, v8, v9 offset0:56 offset1:124
	ds_read_b128 v[8:11], v60 offset:224
	ds_read_b128 v[12:15], v60 offset:240
	ds_read_b128 v[16:19], v61 offset:224
	ds_read_b128 v[20:23], v61 offset:240
	v_lshlrev_b32_e32 v25, 16, v4
	v_lshlrev_b32_e32 v24, 16, v0
	v_and_b32_e32 v27, 0xffff0000, v4
	v_and_b32_e32 v26, 0xffff0000, v0
	v_pk_fma_f32 v[24:25], v[56:57], s[44:45], v[24:25] op_sel_hi:[1,0,1] neg_lo:[1,0,0] neg_hi:[1,0,0]
	v_pk_fma_f32 v[26:27], v[56:57], s[44:45], v[26:27] op_sel_hi:[1,0,1] neg_lo:[1,0,0] neg_hi:[1,0,0]
	v_pk_mul_f32 v[24:25], v[24:25], v[58:59]
	v_pk_mul_f32 v[26:27], v[26:27], v[58:59]
	s_waitcnt lgkmcnt(1)
	v_pk_fma_f32 v[24:25], v[24:25], v[8:9], v[16:17] op_sel_hi:[1,0,0]
	v_pk_fma_f32 v[8:9], v[26:27], v[8:9], v[16:17] op_sel:[0,1,1]
	v_cvt_pk_bf16_f32 v0, v24, v25
	v_cvt_pk_bf16_f32 v4, v8, v9
	v_add_u32_e32 v8, 0x3600, v161
	ds_write2_b32 v8, v0, v4 offset0:80 offset1:148
	v_lshlrev_b32_e32 v9, 16, v5
	v_lshlrev_b32_e32 v8, 16, v1
	v_pk_fma_f32 v[8:9], v[56:57], s[44:45], v[8:9] op_sel_hi:[1,0,1] neg_lo:[1,0,0] neg_hi:[1,0,0]
	v_and_b32_e32 v5, 0xffff0000, v5
	v_and_b32_e32 v4, 0xffff0000, v1
	v_pk_mul_f32 v[8:9], v[8:9], v[58:59]
	v_pk_fma_f32 v[0:1], v[56:57], s[44:45], v[4:5] op_sel_hi:[1,0,1] neg_lo:[1,0,0] neg_hi:[1,0,0]
	v_pk_fma_f32 v[8:9], v[8:9], v[10:11], v[18:19] op_sel_hi:[1,0,0]
	v_pk_mul_f32 v[0:1], v[0:1], v[58:59]
	v_mov_b32_e32 v4, v11
	v_mov_b32_e32 v10, v19
	v_pk_fma_f32 v[0:1], v[0:1], v[4:5], v[10:11] op_sel_hi:[1,0,0]
	v_cvt_pk_bf16_f32 v4, v8, v9
	v_cvt_pk_bf16_f32 v0, v0, v1
	v_add_u32_e32 v1, 0x3800, v161
	ds_write2_b32 v1, v4, v0 offset0:88 offset1:156
	v_lshlrev_b32_e32 v1, 16, v6
	v_lshlrev_b32_e32 v0, 16, v2
	v_and_b32_e32 v5, 0xffff0000, v6
	v_and_b32_e32 v4, 0xffff0000, v2
	v_pk_fma_f32 v[0:1], v[56:57], s[44:45], v[0:1] op_sel_hi:[1,0,1] neg_lo:[1,0,0] neg_hi:[1,0,0]
	v_pk_fma_f32 v[4:5], v[56:57], s[44:45], v[4:5] op_sel_hi:[1,0,1] neg_lo:[1,0,0] neg_hi:[1,0,0]
	v_pk_mul_f32 v[0:1], v[0:1], v[58:59]
	v_pk_mul_f32 v[4:5], v[4:5], v[58:59]
	s_waitcnt lgkmcnt(2)
	v_pk_fma_f32 v[0:1], v[0:1], v[12:13], v[20:21] op_sel_hi:[1,0,0]
	v_pk_fma_f32 v[4:5], v[4:5], v[12:13], v[20:21] op_sel:[0,1,1]
	v_cvt_pk_bf16_f32 v0, v0, v1
	v_cvt_pk_bf16_f32 v1, v4, v5
	v_add_u32_e32 v2, 0x3e00, v161
	ds_write2_b32 v2, v0, v1 offset0:112 offset1:180
	v_lshlrev_b32_e32 v1, 16, v7
	v_lshlrev_b32_e32 v0, 16, v3
	v_and_b32_e32 v5, 0xffff0000, v7
	v_and_b32_e32 v4, 0xffff0000, v3
	v_pk_fma_f32 v[0:1], v[56:57], s[44:45], v[0:1] op_sel_hi:[1,0,1] neg_lo:[1,0,0] neg_hi:[1,0,0]
	v_pk_fma_f32 v[2:3], v[56:57], s[44:45], v[4:5] op_sel_hi:[1,0,1] neg_lo:[1,0,0] neg_hi:[1,0,0]
	v_pk_mul_f32 v[0:1], v[0:1], v[58:59]
	v_pk_mul_f32 v[2:3], v[2:3], v[58:59]
	v_mov_b32_e32 v4, v15
	v_mov_b32_e32 v6, v23
	v_pk_fma_f32 v[0:1], v[0:1], v[14:15], v[22:23] op_sel_hi:[1,0,0]
	v_pk_fma_f32 v[2:3], v[2:3], v[4:5], v[6:7] op_sel_hi:[1,0,0]
	v_cvt_pk_bf16_f32 v0, v0, v1
	v_cvt_pk_bf16_f32 v1, v2, v3
	v_add_u32_e32 v2, 0x4000, v161
	ds_write2_b32 v2, v0, v1 offset0:120 offset1:188
	v_add_u32_e32 v0, v163, v169
	ds_read_b128 v[100:103], v0
	ds_read_b128 v[96:99], v0 offset:32
	ds_read_b128 v[92:95], v0 offset:64
	ds_read_b128 v[88:91], v0 offset:96
	ds_read_b128 v[84:87], v0 offset:128
	ds_read_b128 v[80:83], v0 offset:160
	ds_read_b128 v[72:75], v0 offset:192
	ds_read_b128 v[64:67], v0 offset:224
	v_add_u32_e32 v0, v163, v171
	v_or_b32_e32 v1, s20, v167
	ds_read_b128 v[124:127], v0
	ds_read_b128 v[120:123], v0 offset:32
	ds_read_b128 v[116:119], v0 offset:64
	ds_read_b128 v[112:115], v0 offset:96
	ds_read_b128 v[108:111], v0 offset:128
	ds_read_b128 v[104:107], v0 offset:160
	ds_read_b128 v[76:79], v0 offset:192
	ds_read_b128 v[68:71], v0 offset:224
	v_or_b32_e32 v0, s19, v157
	v_lshlrev_b32_e32 v192, 1, v1
	v_lshl_add_u64 v[206:207], s[36:37], 0, v[192:193]
	v_lshl_add_u64 v[204:205], s[80:81], 0, v[192:193]
	v_lshl_add_u64 v[202:203], s[4:5], 0, v[192:193]
	v_lshlrev_b32_e32 v192, 8, v0
	v_lshl_add_u64 v[128:129], v[158:159], 0, v[192:193]
	global_load_dwordx4 v[0:3], v[128:129], off
	global_load_dwordx4 v[32:35], v[128:129], off offset:32
	v_add_co_u32_e32 v4, vcc, s57, v128
	v_readlane_b32 s20, v253, 61
	s_nop 0
	v_addc_co_u32_e32 v5, vcc, 0, v129, vcc
	global_load_dwordx4 v[36:39], v[4:5], off
	global_load_dwordx4 v[130:133], v[4:5], off offset:32
	global_load_dwordx4 v[134:137], v[4:5], off offset:64
	global_load_dwordx4 v[138:141], v[4:5], off offset:96
	v_readlane_b32 s21, v253, 62
	s_waitcnt vmcnt(3) lgkmcnt(14)
	v_mfma_f32_32x32x16_bf16 v[48:63], v[100:103], v[36:39], 0
	v_and_b32_e32 v4, 0xffff0000, v0
	v_cndmask_b32_e64 v4, v0, v4, s[52:53]
	v_and_b32_e32 v4, 0xffff, v4
	v_cndmask_b32_e64 v0, v4, v0, s[20:21]
	v_readlane_b32 s20, v253, 59
	v_and_b32_e32 v4, 0xffff0000, v1
	v_readlane_b32 s21, v253, 60
	v_and_b32_e32 v40, 0xffff0000, v32
	s_waitcnt vmcnt(2)
	v_mfma_f32_32x32x16_bf16 v[48:63], v[96:99], v[130:133], v[48:63]
	v_cndmask_b32_e64 v1, v1, v4, s[20:21]
	v_readlane_b32 s20, v253, 57
	v_and_b32_e32 v4, 0xffff, v1
	v_readlane_b32 s21, v253, 58
	s_nop 1
	v_cndmask_b32_e64 v1, v1, v4, s[20:21]
	v_readlane_b32 s20, v253, 55
	v_and_b32_e32 v4, 0xffff0000, v2
	v_readlane_b32 s21, v253, 56
	s_nop 1
	v_cndmask_b32_e64 v2, v2, v4, s[20:21]
	v_readlane_b32 s20, v253, 53
	v_and_b32_e32 v4, 0xffff, v2
	v_readlane_b32 s21, v253, 54
	s_nop 1
	v_cndmask_b32_e64 v2, v2, v4, s[20:21]
	v_readlane_b32 s20, v254, 13
	v_readlane_b32 s21, v254, 14
	v_and_b32_e32 v4, 0xffff0000, v3
	v_cndmask_b32_e64 v3, v3, v4, s[86:87]
	v_cndmask_b32_e64 v32, v32, v40, s[20:21]
	v_readlane_b32 s20, v254, 11
	v_and_b32_e32 v40, 0xffff, v32
	v_readlane_b32 s21, v254, 12
	v_and_b32_e32 v4, 0xffff, v3
	v_cndmask_b32_e64 v3, v3, v4, s[84:85]
	v_cndmask_b32_e64 v32, v32, v40, s[20:21]
	v_readlane_b32 s20, v254, 9
	v_and_b32_e32 v40, 0xffff0000, v33
	v_readlane_b32 s21, v254, 10
	v_mfma_f32_32x32x16_bf16 v[16:31], v[100:103], v[0:3], 0
	s_nop 0
	v_cndmask_b32_e64 v33, v33, v40, s[20:21]
	v_readlane_b32 s20, v254, 7
	v_and_b32_e32 v40, 0xffff, v33
	v_readlane_b32 s21, v254, 8
	s_nop 1
	v_cndmask_b32_e64 v33, v33, v40, s[20:21]
	v_readlane_b32 s20, v254, 5
	s_waitcnt lgkmcnt(7)
	v_mfma_f32_32x32x16_bf16 v[0:15], v[124:127], v[0:3], 0
	v_and_b32_e32 v40, 0xffff0000, v34
	v_readlane_b32 s21, v254, 6
	s_nop 1
	v_cndmask_b32_e64 v34, v34, v40, s[20:21]
	v_readlane_b32 s20, v254, 3
	v_and_b32_e32 v40, 0xffff, v34
	v_readlane_b32 s21, v254, 4
	s_nop 1
	v_cndmask_b32_e64 v34, v34, v40, s[20:21]
	v_readlane_b32 s20, v254, 1
	v_and_b32_e32 v40, 0xffff0000, v35
	v_readlane_b32 s21, v254, 2
	s_nop 1
	v_cndmask_b32_e64 v35, v35, v40, s[20:21]
	v_readlane_b32 s20, v253, 63
	v_and_b32_e32 v40, 0xffff, v35
	v_readlane_b32 s21, v254, 0
	s_nop 1
	v_cndmask_b32_e64 v35, v35, v40, s[20:21]
	v_readlane_b32 s20, v254, 29
	v_readlane_b32 s21, v254, 30
	v_mfma_f32_32x32x16_bf16 v[16:31], v[96:99], v[32:35], v[16:31]
	s_waitcnt lgkmcnt(6)
	v_mfma_f32_32x32x16_bf16 v[0:15], v[120:123], v[32:35], v[0:15]
	s_nop 9
	ds_write_b128 v175, v[16:19]
	ds_write_b128 v175, v[20:23] offset:16
	ds_write_b128 v175, v[24:27] offset:32
	ds_write_b128 v175, v[28:31] offset:48
	ds_write_b128 v175, v[0:3] offset:128
	ds_write_b128 v175, v[4:7] offset:144
	ds_write_b128 v175, v[8:11] offset:160
	ds_write_b128 v175, v[12:15] offset:176
	v_or_b32_e32 v8, s19, v160
	v_lshlrev_b32_e32 v179, 2, v8
	v_lshlrev_b64 v[8:9], 11, v[154:155]
	v_mfma_f32_32x32x16_bf16 v[32:47], v[124:127], v[36:39], 0
	v_lshl_add_u64 v[10:11], v[206:207], 0, v[8:9]
	v_lshl_add_u64 v[8:9], v[204:205], 0, v[8:9]
	v_mfma_f32_32x32x16_bf16 v[32:47], v[120:123], v[130:133], v[32:47]
	s_waitcnt vmcnt(1)
	v_and_b32_e32 v130, 0xffff0000, v134
	v_cndmask_b32_e64 v130, v134, v130, s[20:21]
	v_readlane_b32 s20, v254, 27
	v_and_b32_e32 v131, 0xffff, v130
	v_readlane_b32 s21, v254, 28
	s_nop 1
	v_cndmask_b32_e64 v130, v130, v131, s[20:21]
	v_readlane_b32 s20, v254, 25
	v_and_b32_e32 v131, 0xffff0000, v135
	v_readlane_b32 s21, v254, 26
	s_nop 1
	v_cndmask_b32_e64 v131, v135, v131, s[20:21]
	v_readlane_b32 s20, v254, 23
	v_and_b32_e32 v132, 0xffff, v131
	v_readlane_b32 s21, v254, 24
	s_nop 1
	v_cndmask_b32_e64 v131, v131, v132, s[20:21]
	v_readlane_b32 s20, v254, 21
	v_and_b32_e32 v132, 0xffff0000, v136
	v_readlane_b32 s21, v254, 22
	s_nop 1
	v_cndmask_b32_e64 v132, v136, v132, s[20:21]
	v_readlane_b32 s20, v254, 19
	v_and_b32_e32 v133, 0xffff, v132
	v_readlane_b32 s21, v254, 20
	v_or_b32_e32 v136, s14, v172
	s_nop 0
	v_cndmask_b32_e64 v132, v132, v133, s[20:21]
	v_readlane_b32 s20, v254, 17
	v_and_b32_e32 v133, 0xffff0000, v137
	v_readlane_b32 s21, v254, 18
	s_nop 1
	v_cndmask_b32_e64 v133, v137, v133, s[20:21]
	v_readlane_b32 s20, v254, 15
	v_and_b32_e32 v134, 0xffff, v133
	v_readlane_b32 s21, v254, 16
	v_mov_b32_e32 v137, s15
	s_nop 0
	v_cndmask_b32_e64 v133, v133, v134, s[20:21]
	v_readlane_b32 s20, v254, 45
	v_readlane_b32 s21, v254, 46
	v_mfma_f32_32x32x16_bf16 v[48:63], v[92:95], v[130:133], v[48:63]
	s_waitcnt lgkmcnt(13)
	v_mfma_f32_32x32x16_bf16 v[32:47], v[116:119], v[130:133], v[32:47]
	s_waitcnt vmcnt(0)
	v_and_b32_e32 v130, 0xffff0000, v138
	v_cndmask_b32_e64 v130, v138, v130, s[20:21]
	v_readlane_b32 s20, v254, 43
	v_and_b32_e32 v131, 0xffff, v130
	v_readlane_b32 s21, v254, 44
	s_nop 1
	v_cndmask_b32_e64 v130, v130, v131, s[20:21]
	v_readlane_b32 s20, v254, 41
	v_and_b32_e32 v131, 0xffff0000, v139
	v_readlane_b32 s21, v254, 42
	s_nop 1
	v_cndmask_b32_e64 v131, v139, v131, s[20:21]
	v_readlane_b32 s20, v254, 39
	v_and_b32_e32 v132, 0xffff, v131
	v_readlane_b32 s21, v254, 40
	s_nop 1
	v_cndmask_b32_e64 v131, v131, v132, s[20:21]
	v_readlane_b32 s20, v254, 37
	v_and_b32_e32 v132, 0xffff0000, v140
	v_readlane_b32 s21, v254, 38
	s_nop 1
	v_cndmask_b32_e64 v132, v140, v132, s[20:21]
	v_readlane_b32 s20, v254, 35
	v_and_b32_e32 v133, 0xffff, v132
	v_readlane_b32 s21, v254, 36
	v_or_b32_e32 v140, s14, v170
	s_nop 0
	v_cndmask_b32_e64 v132, v132, v133, s[20:21]
	v_readlane_b32 s20, v254, 33
	v_and_b32_e32 v133, 0xffff0000, v141
	v_readlane_b32 s21, v254, 34
	s_nop 1
	v_cndmask_b32_e64 v133, v141, v133, s[20:21]
	v_readlane_b32 s20, v254, 31
	v_and_b32_e32 v134, 0xffff, v133
	v_readlane_b32 s21, v254, 32
	v_mov_b32_e32 v141, s15
	s_nop 0
	v_cndmask_b32_e64 v133, v133, v134, s[20:21]
	v_readlane_b32 s20, v254, 59
	v_readlane_b32 s21, v254, 60
	v_mfma_f32_32x32x16_bf16 v[48:63], v[88:91], v[130:133], v[48:63]
	s_waitcnt lgkmcnt(12)
	v_mfma_f32_32x32x16_bf16 v[32:47], v[112:115], v[130:133], v[32:47]
	v_mov_b32_e32 v131, s15
	v_or_b32_e32 v130, s14, v160
	v_lshlrev_b64 v[0:1], 11, v[130:131]
	s_nop 6
	ds_write_b128 v177, v[48:51]
	ds_write_b128 v177, v[52:55] offset:16
	ds_write_b128 v177, v[56:59] offset:32
	ds_write_b128 v177, v[60:63] offset:48
	ds_write_b128 v177, v[32:35] offset:128
	ds_write_b128 v177, v[36:39] offset:144
	ds_write_b128 v177, v[40:43] offset:160
	ds_write_b128 v177, v[44:47] offset:176
	v_lshl_add_u64 v[2:3], v[206:207], 0, v[0:1]
	v_lshl_add_u64 v[0:1], v[204:205], 0, v[0:1]
	global_load_dwordx4 v[4:7], v[2:3], off nt
	global_load_dword v208, v179, s[12:13]
	global_load_dwordx4 v[52:55], v[10:11], off nt
	v_mov_b32_e32 v133, s15
	global_load_dwordx4 v[0:3], v[0:1], off nt
	s_nop 0
	global_load_dwordx4 v[48:51], v[8:9], off nt
	global_load_dword v192, v179, s[12:13] offset:32
	v_lshlrev_b64 v[8:9], 11, v[150:151]
	v_lshl_add_u64 v[10:11], v[206:207], 0, v[8:9]
	v_lshl_add_u64 v[8:9], v[204:205], 0, v[8:9]
	global_load_dwordx4 v[44:47], v[10:11], off nt
	global_load_dwordx4 v[40:43], v[8:9], off nt
	global_load_dword v152, v179, s[12:13] offset:64
	v_lshlrev_b64 v[8:9], 11, v[146:147]
	v_lshl_add_u64 v[10:11], v[206:207], 0, v[8:9]
	v_lshl_add_u64 v[8:9], v[204:205], 0, v[8:9]
	global_load_dwordx4 v[36:39], v[10:11], off nt
	global_load_dwordx4 v[32:35], v[8:9], off nt
	global_load_dword v148, v179, s[12:13] offset:96
	v_lshlrev_b64 v[8:9], 11, v[140:141]
	v_lshl_add_u64 v[10:11], v[206:207], 0, v[8:9]
	v_lshl_add_u64 v[8:9], v[204:205], 0, v[8:9]
	global_load_dwordx4 v[28:31], v[10:11], off nt
	global_load_dwordx4 v[24:27], v[8:9], off nt
	global_load_dword v142, v179, s[12:13] offset:128
	v_lshlrev_b64 v[8:9], 11, v[136:137]
	v_lshl_add_u64 v[10:11], v[206:207], 0, v[8:9]
	v_lshl_add_u64 v[8:9], v[204:205], 0, v[8:9]
	v_or_b32_e32 v132, s14, v174
	global_load_dwordx4 v[20:23], v[10:11], off nt
	global_load_dwordx4 v[16:19], v[8:9], off nt
	global_load_dword v138, v179, s[12:13] offset:160
	v_lshlrev_b64 v[8:9], 11, v[132:133]
	v_lshlrev_b64 v[60:61], 11, v[144:145]
	v_lshl_add_u64 v[10:11], v[206:207], 0, v[8:9]
	v_lshl_add_u64 v[8:9], v[204:205], 0, v[8:9]
	v_lshl_add_u64 v[56:57], v[206:207], 0, v[60:61]
	v_lshl_add_u64 v[60:61], v[204:205], 0, v[60:61]
	global_load_dwordx4 v[12:15], v[10:11], off nt
	s_nop 0
	global_load_dwordx4 v[8:11], v[8:9], off nt
	s_nop 0
	global_load_dword v134, v179, s[12:13] offset:192
	s_nop 0
	global_load_dwordx4 v[56:59], v[56:57], off nt
	s_nop 0
	global_load_dwordx4 v[60:63], v[60:61], off nt
	s_nop 0
	global_load_dword v210, v179, s[12:13] offset:224
	s_waitcnt vmcnt(1)
	ds_read_b128 v[212:215], v173
	ds_read_b128 v[216:219], v173 offset:16
	v_lshlrev_b32_e32 v196, 16, v4
	v_and_b32_e32 v197, 0xffff0000, v4
	v_lshlrev_b32_e32 v4, 16, v5
	s_waitcnt lgkmcnt(1)
	v_pk_add_f32 v[212:213], v[208:209], v[212:213] op_sel_hi:[0,1]
	v_pk_mul_f32 v[196:197], v[212:213], v[196:197]
	v_lshlrev_b32_e32 v212, 16, v0
	v_and_b32_e32 v213, 0xffff0000, v0
	v_pk_mul_f32 v[196:197], v[196:197], v[212:213]
	v_and_b32_e32 v5, 0xffff0000, v5
	v_cvt_pk_bf16_f32 v0, v196, v197
	v_pk_add_f32 v[196:197], v[208:209], v[214:215] op_sel_hi:[0,1]
	v_pk_mul_f32 v[4:5], v[196:197], v[4:5]
	v_lshlrev_b32_e32 v196, 16, v1
	v_and_b32_e32 v197, 0xffff0000, v1
	v_pk_mul_f32 v[4:5], v[4:5], v[196:197]
	s_waitcnt lgkmcnt(0)
	v_pk_add_f32 v[196:197], v[208:209], v[216:217] op_sel_hi:[0,1]
	v_cvt_pk_bf16_f32 v1, v4, v5
	v_lshlrev_b32_e32 v4, 16, v6
	v_and_b32_e32 v5, 0xffff0000, v6
	v_pk_mul_f32 v[4:5], v[196:197], v[4:5]
	v_lshlrev_b32_e32 v196, 16, v2
	v_and_b32_e32 v197, 0xffff0000, v2
	v_pk_mul_f32 v[4:5], v[4:5], v[196:197]
	s_nop 0
	v_cvt_pk_bf16_f32 v2, v4, v5
	v_lshlrev_b32_e32 v4, 16, v7
	v_and_b32_e32 v5, 0xffff0000, v7
	v_pk_add_f32 v[6:7], v[208:209], v[218:219] op_sel_hi:[0,1]
	v_pk_mul_f32 v[4:5], v[6:7], v[4:5]
	v_lshlrev_b32_e32 v6, 16, v3
	v_and_b32_e32 v7, 0xffff0000, v3
	v_pk_mul_f32 v[4:5], v[4:5], v[6:7]
	s_nop 0
	v_cvt_pk_bf16_f32 v3, v4, v5
	v_lshlrev_b64 v[4:5], 12, v[130:131]
	v_lshl_add_u64 v[4:5], v[202:203], 0, v[4:5]
	global_store_dwordx4 v[4:5], v[0:3], off
	ds_read_b128 v[0:3], v173 offset:2176
	ds_read_b128 v[4:7], v173 offset:2192
	v_lshlrev_b32_e32 v130, 16, v52
	v_and_b32_e32 v131, 0xffff0000, v52
	v_lshlrev_b32_e32 v52, 16, v53
	s_waitcnt lgkmcnt(1)
	v_pk_add_f32 v[0:1], v[192:193], v[0:1] op_sel_hi:[0,1]
	v_and_b32_e32 v53, 0xffff0000, v53
	v_pk_add_f32 v[2:3], v[192:193], v[2:3] op_sel_hi:[0,1]
	v_pk_mul_f32 v[0:1], v[0:1], v[130:131]
	v_lshlrev_b32_e32 v130, 16, v48
	v_and_b32_e32 v131, 0xffff0000, v48
	v_pk_mul_f32 v[2:3], v[2:3], v[52:53]
	v_lshlrev_b32_e32 v48, 16, v49
	v_and_b32_e32 v49, 0xffff0000, v49
	v_pk_mul_f32 v[0:1], v[0:1], v[130:131]
	v_pk_mul_f32 v[2:3], v[2:3], v[48:49]
	v_cvt_pk_bf16_f32 v0, v0, v1
	v_cvt_pk_bf16_f32 v1, v2, v3
	v_lshlrev_b32_e32 v2, 16, v54
	v_and_b32_e32 v3, 0xffff0000, v54
	s_waitcnt lgkmcnt(0)
	v_pk_add_f32 v[4:5], v[192:193], v[4:5] op_sel_hi:[0,1]
	v_pk_mul_f32 v[2:3], v[4:5], v[2:3]
	v_lshlrev_b32_e32 v4, 16, v50
	v_and_b32_e32 v5, 0xffff0000, v50
	v_pk_mul_f32 v[2:3], v[2:3], v[4:5]
	v_lshlrev_b32_e32 v4, 16, v55
	v_and_b32_e32 v5, 0xffff0000, v55
	v_pk_add_f32 v[6:7], v[192:193], v[6:7] op_sel_hi:[0,1]
	v_pk_mul_f32 v[4:5], v[6:7], v[4:5]
	v_lshlrev_b32_e32 v6, 16, v51
	v_and_b32_e32 v7, 0xffff0000, v51
	v_pk_mul_f32 v[4:5], v[4:5], v[6:7]
	v_cvt_pk_bf16_f32 v2, v2, v3
	v_cvt_pk_bf16_f32 v3, v4, v5
	v_lshlrev_b64 v[4:5], 12, v[154:155]
	v_lshl_add_u64 v[4:5], v[202:203], 0, v[4:5]
	global_store_dwordx4 v[4:5], v[0:3], off
	ds_read_b128 v[0:3], v173 offset:4352
	ds_read_b128 v[4:7], v173 offset:4368
	v_lshlrev_b32_e32 v48, 16, v44
	v_and_b32_e32 v49, 0xffff0000, v44
	v_lshlrev_b32_e32 v44, 16, v45
	s_waitcnt lgkmcnt(1)
	v_pk_add_f32 v[0:1], v[152:153], v[0:1] op_sel_hi:[0,1]
	v_and_b32_e32 v45, 0xffff0000, v45
	v_pk_add_f32 v[2:3], v[152:153], v[2:3] op_sel_hi:[0,1]
	v_pk_mul_f32 v[0:1], v[0:1], v[48:49]
	v_lshlrev_b32_e32 v48, 16, v40
	v_and_b32_e32 v49, 0xffff0000, v40
	v_pk_mul_f32 v[2:3], v[2:3], v[44:45]
	v_lshlrev_b32_e32 v40, 16, v41
	v_and_b32_e32 v41, 0xffff0000, v41
	v_pk_mul_f32 v[0:1], v[0:1], v[48:49]
	v_pk_mul_f32 v[2:3], v[2:3], v[40:41]
	v_cvt_pk_bf16_f32 v0, v0, v1
	v_cvt_pk_bf16_f32 v1, v2, v3
	v_lshlrev_b32_e32 v2, 16, v46
	v_and_b32_e32 v3, 0xffff0000, v46
	s_waitcnt lgkmcnt(0)
	v_pk_add_f32 v[4:5], v[152:153], v[4:5] op_sel_hi:[0,1]
	v_pk_mul_f32 v[2:3], v[4:5], v[2:3]
	v_lshlrev_b32_e32 v4, 16, v42
	v_and_b32_e32 v5, 0xffff0000, v42
	v_pk_mul_f32 v[2:3], v[2:3], v[4:5]
	v_lshlrev_b32_e32 v4, 16, v47
	v_and_b32_e32 v5, 0xffff0000, v47
	v_pk_add_f32 v[6:7], v[152:153], v[6:7] op_sel_hi:[0,1]
	v_pk_mul_f32 v[4:5], v[6:7], v[4:5]
	v_lshlrev_b32_e32 v6, 16, v43
	v_and_b32_e32 v7, 0xffff0000, v43
	v_pk_mul_f32 v[4:5], v[4:5], v[6:7]
	v_cvt_pk_bf16_f32 v2, v2, v3
	v_cvt_pk_bf16_f32 v3, v4, v5
	v_lshlrev_b64 v[4:5], 12, v[150:151]
	v_lshl_add_u64 v[4:5], v[202:203], 0, v[4:5]
	global_store_dwordx4 v[4:5], v[0:3], off
	ds_read_b128 v[0:3], v173 offset:6528
	ds_read_b128 v[4:7], v173 offset:6544
	v_lshlrev_b32_e32 v40, 16, v36
	v_and_b32_e32 v41, 0xffff0000, v36
	v_lshlrev_b32_e32 v36, 16, v37
	s_waitcnt lgkmcnt(1)
	v_pk_add_f32 v[0:1], v[148:149], v[0:1] op_sel_hi:[0,1]
	v_and_b32_e32 v37, 0xffff0000, v37
	v_pk_add_f32 v[2:3], v[148:149], v[2:3] op_sel_hi:[0,1]
	v_pk_mul_f32 v[0:1], v[0:1], v[40:41]
	v_lshlrev_b32_e32 v40, 16, v32
	v_and_b32_e32 v41, 0xffff0000, v32
	v_pk_mul_f32 v[2:3], v[2:3], v[36:37]
	v_lshlrev_b32_e32 v32, 16, v33
	v_and_b32_e32 v33, 0xffff0000, v33
	v_pk_mul_f32 v[0:1], v[0:1], v[40:41]
	v_pk_mul_f32 v[2:3], v[2:3], v[32:33]
	v_cvt_pk_bf16_f32 v0, v0, v1
	v_cvt_pk_bf16_f32 v1, v2, v3
	v_lshlrev_b32_e32 v2, 16, v38
	v_and_b32_e32 v3, 0xffff0000, v38
	s_waitcnt lgkmcnt(0)
	v_pk_add_f32 v[4:5], v[148:149], v[4:5] op_sel_hi:[0,1]
	v_pk_mul_f32 v[2:3], v[4:5], v[2:3]
	v_lshlrev_b32_e32 v4, 16, v34
	v_and_b32_e32 v5, 0xffff0000, v34
	v_pk_mul_f32 v[2:3], v[2:3], v[4:5]
	v_lshlrev_b32_e32 v4, 16, v39
	v_and_b32_e32 v5, 0xffff0000, v39
	v_pk_add_f32 v[6:7], v[148:149], v[6:7] op_sel_hi:[0,1]
	v_pk_mul_f32 v[4:5], v[6:7], v[4:5]
	v_lshlrev_b32_e32 v6, 16, v35
	v_and_b32_e32 v7, 0xffff0000, v35
	v_pk_mul_f32 v[4:5], v[4:5], v[6:7]
	v_cvt_pk_bf16_f32 v2, v2, v3
	v_cvt_pk_bf16_f32 v3, v4, v5
	v_lshlrev_b64 v[4:5], 12, v[146:147]
	v_lshl_add_u64 v[4:5], v[202:203], 0, v[4:5]
	global_store_dwordx4 v[4:5], v[0:3], off
	ds_read_b128 v[0:3], v173 offset:8704
	ds_read_b128 v[4:7], v173 offset:8720
	v_lshlrev_b32_e32 v32, 16, v28
	v_and_b32_e32 v33, 0xffff0000, v28
	v_lshlrev_b32_e32 v28, 16, v29
	s_waitcnt lgkmcnt(1)
	v_pk_add_f32 v[0:1], v[142:143], v[0:1] op_sel_hi:[0,1]
	v_and_b32_e32 v29, 0xffff0000, v29
	v_pk_add_f32 v[2:3], v[142:143], v[2:3] op_sel_hi:[0,1]
	v_pk_mul_f32 v[0:1], v[0:1], v[32:33]
	v_lshlrev_b32_e32 v32, 16, v24
	v_and_b32_e32 v33, 0xffff0000, v24
	v_pk_mul_f32 v[2:3], v[2:3], v[28:29]
	v_lshlrev_b32_e32 v24, 16, v25
	v_and_b32_e32 v25, 0xffff0000, v25
	v_pk_mul_f32 v[0:1], v[0:1], v[32:33]
	v_pk_mul_f32 v[2:3], v[2:3], v[24:25]
	v_cvt_pk_bf16_f32 v0, v0, v1
	v_cvt_pk_bf16_f32 v1, v2, v3
	v_lshlrev_b32_e32 v2, 16, v30
	v_and_b32_e32 v3, 0xffff0000, v30
	s_waitcnt lgkmcnt(0)
	v_pk_add_f32 v[4:5], v[142:143], v[4:5] op_sel_hi:[0,1]
	v_pk_mul_f32 v[2:3], v[4:5], v[2:3]
	v_lshlrev_b32_e32 v4, 16, v26
	v_and_b32_e32 v5, 0xffff0000, v26
	v_pk_mul_f32 v[2:3], v[2:3], v[4:5]
	v_lshlrev_b32_e32 v4, 16, v31
	v_and_b32_e32 v5, 0xffff0000, v31
	v_pk_add_f32 v[6:7], v[142:143], v[6:7] op_sel_hi:[0,1]
	v_pk_mul_f32 v[4:5], v[6:7], v[4:5]
	v_lshlrev_b32_e32 v6, 16, v27
	v_and_b32_e32 v7, 0xffff0000, v27
	v_pk_mul_f32 v[4:5], v[4:5], v[6:7]
	v_cvt_pk_bf16_f32 v2, v2, v3
	v_cvt_pk_bf16_f32 v3, v4, v5
	v_lshlrev_b64 v[4:5], 12, v[140:141]
	v_lshl_add_u64 v[4:5], v[202:203], 0, v[4:5]
	global_store_dwordx4 v[4:5], v[0:3], off
	ds_read_b128 v[0:3], v173 offset:10880
	ds_read_b128 v[4:7], v173 offset:10896
	v_lshlrev_b32_e32 v24, 16, v20
	v_and_b32_e32 v25, 0xffff0000, v20
	v_lshlrev_b32_e32 v20, 16, v21
	s_waitcnt lgkmcnt(1)
	v_pk_add_f32 v[0:1], v[138:139], v[0:1] op_sel_hi:[0,1]
	v_and_b32_e32 v21, 0xffff0000, v21
	v_pk_add_f32 v[2:3], v[138:139], v[2:3] op_sel_hi:[0,1]
	v_pk_mul_f32 v[0:1], v[0:1], v[24:25]
	v_lshlrev_b32_e32 v24, 16, v16
	v_and_b32_e32 v25, 0xffff0000, v16
	v_pk_mul_f32 v[2:3], v[2:3], v[20:21]
	v_lshlrev_b32_e32 v16, 16, v17
	v_and_b32_e32 v17, 0xffff0000, v17
	v_pk_mul_f32 v[0:1], v[0:1], v[24:25]
	v_pk_mul_f32 v[2:3], v[2:3], v[16:17]
	v_cvt_pk_bf16_f32 v0, v0, v1
	v_cvt_pk_bf16_f32 v1, v2, v3
	v_lshlrev_b32_e32 v2, 16, v22
	v_and_b32_e32 v3, 0xffff0000, v22
	s_waitcnt lgkmcnt(0)
	v_pk_add_f32 v[4:5], v[138:139], v[4:5] op_sel_hi:[0,1]
	v_pk_mul_f32 v[2:3], v[4:5], v[2:3]
	v_lshlrev_b32_e32 v4, 16, v18
	v_and_b32_e32 v5, 0xffff0000, v18
	v_pk_mul_f32 v[2:3], v[2:3], v[4:5]
	v_lshlrev_b32_e32 v4, 16, v23
	v_and_b32_e32 v5, 0xffff0000, v23
	v_pk_add_f32 v[6:7], v[138:139], v[6:7] op_sel_hi:[0,1]
	v_pk_mul_f32 v[4:5], v[6:7], v[4:5]
	v_lshlrev_b32_e32 v6, 16, v19
	v_and_b32_e32 v7, 0xffff0000, v19
	v_pk_mul_f32 v[4:5], v[4:5], v[6:7]
	v_cvt_pk_bf16_f32 v2, v2, v3
	v_cvt_pk_bf16_f32 v3, v4, v5
	v_lshlrev_b64 v[4:5], 12, v[136:137]
	v_lshl_add_u64 v[4:5], v[202:203], 0, v[4:5]
	global_store_dwordx4 v[4:5], v[0:3], off
	ds_read_b128 v[0:3], v173 offset:13056
	ds_read_b128 v[4:7], v173 offset:13072
	v_lshlrev_b32_e32 v16, 16, v12
	v_and_b32_e32 v17, 0xffff0000, v12
	v_lshlrev_b32_e32 v12, 16, v13
	s_waitcnt lgkmcnt(1)
	v_pk_add_f32 v[0:1], v[134:135], v[0:1] op_sel_hi:[0,1]
	v_and_b32_e32 v13, 0xffff0000, v13
	v_pk_add_f32 v[2:3], v[134:135], v[2:3] op_sel_hi:[0,1]
	v_pk_mul_f32 v[0:1], v[0:1], v[16:17]
	v_lshlrev_b32_e32 v16, 16, v8
	v_and_b32_e32 v17, 0xffff0000, v8
	v_pk_mul_f32 v[2:3], v[2:3], v[12:13]
	v_lshlrev_b32_e32 v8, 16, v9
	v_and_b32_e32 v9, 0xffff0000, v9
	v_pk_mul_f32 v[0:1], v[0:1], v[16:17]
	v_pk_mul_f32 v[2:3], v[2:3], v[8:9]
	v_cvt_pk_bf16_f32 v0, v0, v1
	v_cvt_pk_bf16_f32 v1, v2, v3
	v_lshlrev_b32_e32 v2, 16, v14
	v_and_b32_e32 v3, 0xffff0000, v14
	s_waitcnt lgkmcnt(0)
	v_pk_add_f32 v[4:5], v[134:135], v[4:5] op_sel_hi:[0,1]
	v_pk_mul_f32 v[2:3], v[4:5], v[2:3]
	v_lshlrev_b32_e32 v4, 16, v10
	v_and_b32_e32 v5, 0xffff0000, v10
	v_pk_mul_f32 v[2:3], v[2:3], v[4:5]
	v_lshlrev_b32_e32 v4, 16, v15
	v_and_b32_e32 v5, 0xffff0000, v15
	v_pk_add_f32 v[6:7], v[134:135], v[6:7] op_sel_hi:[0,1]
	v_pk_mul_f32 v[4:5], v[6:7], v[4:5]
	v_lshlrev_b32_e32 v6, 16, v11
	v_and_b32_e32 v7, 0xffff0000, v11
	v_pk_mul_f32 v[4:5], v[4:5], v[6:7]
	v_cvt_pk_bf16_f32 v2, v2, v3
	v_cvt_pk_bf16_f32 v3, v4, v5
	v_lshlrev_b64 v[4:5], 12, v[132:133]
	v_lshl_add_u64 v[4:5], v[202:203], 0, v[4:5]
	global_store_dwordx4 v[4:5], v[0:3], off
	ds_read_b128 v[0:3], v173 offset:15232
	ds_read_b128 v[4:7], v173 offset:15248
	v_lshlrev_b32_e32 v8, 16, v56
	v_and_b32_e32 v9, 0xffff0000, v56
	s_waitcnt vmcnt(7) lgkmcnt(1)
	v_pk_add_f32 v[0:1], v[210:211], v[0:1] op_sel_hi:[0,1]
	v_pk_mul_f32 v[0:1], v[0:1], v[8:9]
	v_lshlrev_b32_e32 v8, 16, v60
	v_and_b32_e32 v9, 0xffff0000, v60
	v_pk_mul_f32 v[0:1], v[0:1], v[8:9]
	v_lshlrev_b32_e32 v8, 16, v57
	v_and_b32_e32 v9, 0xffff0000, v57
	v_pk_add_f32 v[2:3], v[210:211], v[2:3] op_sel_hi:[0,1]
	v_pk_mul_f32 v[2:3], v[2:3], v[8:9]
	v_lshlrev_b32_e32 v8, 16, v61
	v_and_b32_e32 v9, 0xffff0000, v61
	v_pk_mul_f32 v[2:3], v[2:3], v[8:9]
	v_cvt_pk_bf16_f32 v0, v0, v1
	v_cvt_pk_bf16_f32 v1, v2, v3
	v_lshlrev_b32_e32 v2, 16, v58
	v_and_b32_e32 v3, 0xffff0000, v58
	s_waitcnt lgkmcnt(0)
	v_pk_add_f32 v[4:5], v[210:211], v[4:5] op_sel_hi:[0,1]
	v_pk_mul_f32 v[2:3], v[4:5], v[2:3]
	v_lshlrev_b32_e32 v4, 16, v62
	v_and_b32_e32 v5, 0xffff0000, v62
	v_pk_mul_f32 v[2:3], v[2:3], v[4:5]
	v_lshlrev_b32_e32 v4, 16, v59
	v_and_b32_e32 v5, 0xffff0000, v59
	v_pk_add_f32 v[6:7], v[210:211], v[6:7] op_sel_hi:[0,1]
	v_pk_mul_f32 v[4:5], v[6:7], v[4:5]
	v_lshlrev_b32_e32 v6, 16, v63
	v_and_b32_e32 v7, 0xffff0000, v63
	v_pk_mul_f32 v[4:5], v[4:5], v[6:7]
	v_cvt_pk_bf16_f32 v2, v2, v3
	v_cvt_pk_bf16_f32 v3, v4, v5
	v_lshlrev_b64 v[4:5], 12, v[144:145]
	v_lshl_add_u64 v[4:5], v[202:203], 0, v[4:5]
	global_store_dwordx4 v[4:5], v[0:3], off
	v_add_co_u32_e32 v4, vcc, s25, v128
	s_nop 1
	v_addc_co_u32_e32 v5, vcc, 0, v129, vcc
	global_load_dwordx4 v[0:3], v[4:5], off
	global_load_dwordx4 v[52:55], v[4:5], off offset:32
	global_load_dwordx4 v[48:51], v[4:5], off offset:64
	global_load_dwordx4 v[44:47], v[4:5], off offset:96
	global_load_dwordx4 v[40:43], v[4:5], off offset:128
	global_load_dwordx4 v[36:39], v[4:5], off offset:160
	v_add_co_u32_e32 v4, vcc, s99, v128
	s_waitcnt vmcnt(5)
	v_mfma_f32_32x32x16_bf16 v[16:31], v[100:103], v[0:3], 0
	v_addc_co_u32_e32 v5, vcc, 0, v129, vcc
	global_load_dwordx4 v[32:35], v[4:5], off
	global_load_dwordx4 v[152:155], v[4:5], off offset:32
	global_load_dwordx4 v[148:151], v[4:5], off offset:64
	global_load_dwordx4 v[144:147], v[4:5], off offset:96
	global_load_dwordx4 v[140:143], v[4:5], off offset:128
	global_load_dwordx4 v[136:139], v[4:5], off offset:160
	global_load_dwordx4 v[132:135], v[4:5], off offset:192
	global_load_dwordx4 v[128:131], v[4:5], off offset:224
	v_mfma_f32_32x32x16_bf16 v[0:15], v[124:127], v[0:3], 0
	s_waitcnt vmcnt(12)
	v_mfma_f32_32x32x16_bf16 v[16:31], v[96:99], v[52:55], v[16:31]
	v_mfma_f32_32x32x16_bf16 v[0:15], v[120:123], v[52:55], v[0:15]
	s_waitcnt vmcnt(11)
	v_mfma_f32_32x32x16_bf16 v[16:31], v[92:95], v[48:51], v[16:31]
	v_mfma_f32_32x32x16_bf16 v[0:15], v[116:119], v[48:51], v[0:15]
	s_waitcnt vmcnt(10)
	v_mfma_f32_32x32x16_bf16 v[16:31], v[88:91], v[44:47], v[16:31]
	v_mfma_f32_32x32x16_bf16 v[0:15], v[112:115], v[44:47], v[0:15]
	s_waitcnt vmcnt(9)
	v_and_b32_e32 v44, 0xffff0000, v40
	v_cndmask_b32_e64 v40, v40, v44, s[52:53]
	v_and_b32_e32 v44, 0xffff, v40
	v_cndmask_b32_e64 v40, v40, v44, s[20:21]
	v_readlane_b32 s20, v254, 57
	v_and_b32_e32 v44, 0xffff0000, v41
	v_readlane_b32 s21, v254, 58
	s_waitcnt vmcnt(7)
	v_mfma_f32_32x32x16_bf16 v[48:63], v[100:103], v[32:35], 0
	v_cndmask_b32_e64 v41, v41, v44, s[20:21]
	v_readlane_b32 s20, v254, 55
	v_and_b32_e32 v44, 0xffff, v41
	v_readlane_b32 s21, v254, 56
	s_nop 1
	v_cndmask_b32_e64 v41, v41, v44, s[20:21]
	v_readlane_b32 s20, v254, 53
	v_and_b32_e32 v44, 0xffff0000, v42
	v_readlane_b32 s21, v254, 54
	s_waitcnt vmcnt(6)
	v_mfma_f32_32x32x16_bf16 v[48:63], v[96:99], v[152:155], v[48:63]
	v_cndmask_b32_e64 v42, v42, v44, s[20:21]
	v_readlane_b32 s20, v254, 51
	v_and_b32_e32 v44, 0xffff, v42
	v_readlane_b32 s21, v254, 52
	s_nop 1
	v_cndmask_b32_e64 v42, v42, v44, s[20:21]
	v_readlane_b32 s20, v254, 49
	v_and_b32_e32 v44, 0xffff0000, v43
	v_readlane_b32 s21, v254, 50
	s_waitcnt vmcnt(5)
	v_mfma_f32_32x32x16_bf16 v[48:63], v[92:95], v[148:151], v[48:63]
	v_mov_b32_e32 v93, s15
	v_cndmask_b32_e64 v43, v43, v44, s[20:21]
	v_readlane_b32 s20, v254, 47
	v_and_b32_e32 v44, 0xffff, v43
	v_readlane_b32 s21, v254, 48
	v_or_b32_e32 v92, s14, v162
	s_nop 0
	v_cndmask_b32_e64 v43, v43, v44, s[20:21]
	v_readlane_b32 s20, v255, 11
	v_readlane_b32 s21, v255, 12
	v_mfma_f32_32x32x16_bf16 v[16:31], v[84:87], v[40:43], v[16:31]
	v_mfma_f32_32x32x16_bf16 v[0:15], v[108:111], v[40:43], v[0:15]
	v_and_b32_e32 v40, 0xffff0000, v36
	v_cndmask_b32_e64 v36, v36, v40, s[20:21]
	v_readlane_b32 s20, v255, 9
	v_and_b32_e32 v40, 0xffff, v36
	v_readlane_b32 s21, v255, 10
	s_nop 1
	v_cndmask_b32_e64 v36, v36, v40, s[20:21]
	v_readlane_b32 s20, v255, 7
	v_and_b32_e32 v40, 0xffff0000, v37
	v_readlane_b32 s21, v255, 8
	s_waitcnt vmcnt(4)
	v_mfma_f32_32x32x16_bf16 v[48:63], v[88:91], v[144:147], v[48:63]
	v_mov_b32_e32 v89, s15
	v_cndmask_b32_e64 v37, v37, v40, s[20:21]
	v_readlane_b32 s20, v255, 5
	v_and_b32_e32 v40, 0xffff, v37
	v_readlane_b32 s21, v255, 6
	v_or_b32_e32 v88, s14, v178
	s_nop 0
	v_cndmask_b32_e64 v37, v37, v40, s[20:21]
	v_readlane_b32 s20, v255, 3
	v_and_b32_e32 v40, 0xffff0000, v38
	v_readlane_b32 s21, v255, 4
	s_waitcnt vmcnt(3)
	v_mfma_f32_32x32x16_bf16 v[48:63], v[84:87], v[140:143], v[48:63]
	v_mov_b32_e32 v85, s15
	v_cndmask_b32_e64 v38, v38, v40, s[20:21]
	v_readlane_b32 s20, v255, 1
	v_and_b32_e32 v40, 0xffff, v38
	v_readlane_b32 s21, v255, 2
	s_nop 1
	v_cndmask_b32_e64 v38, v38, v40, s[20:21]
	v_readlane_b32 s20, v254, 63
	v_and_b32_e32 v40, 0xffff0000, v39
	v_readlane_b32 s21, v255, 0
	s_waitcnt vmcnt(2)
	v_mfma_f32_32x32x16_bf16 v[48:63], v[80:83], v[136:139], v[48:63]
	v_cndmask_b32_e64 v39, v39, v40, s[20:21]
	v_readlane_b32 s20, v254, 61
	v_and_b32_e32 v40, 0xffff, v39
	v_readlane_b32 s21, v254, 62
	s_nop 1
	v_cndmask_b32_e64 v39, v39, v40, s[20:21]
	v_readlane_b32 s20, v255, 27
	v_readlane_b32 s21, v255, 28
	v_mfma_f32_32x32x16_bf16 v[16:31], v[80:83], v[36:39], v[16:31]
	s_waitcnt vmcnt(1)
	v_and_b32_e32 v80, 0xffff0000, v132
	v_cndmask_b32_e64 v80, v132, v80, s[20:21]
	v_readlane_b32 s20, v255, 25
	v_and_b32_e32 v81, 0xffff, v80
	v_readlane_b32 s21, v255, 26
	v_mfma_f32_32x32x16_bf16 v[0:15], v[104:107], v[36:39], v[0:15]
	s_nop 0
	v_cndmask_b32_e64 v80, v80, v81, s[20:21]
	v_readlane_b32 s20, v255, 23
	v_and_b32_e32 v81, 0xffff0000, v133
	v_readlane_b32 s21, v255, 24
	s_nop 1
	v_cndmask_b32_e64 v81, v133, v81, s[20:21]
	v_mfma_f32_32x32x16_bf16 v[32:47], v[124:127], v[32:35], 0
	v_readlane_b32 s20, v255, 21
	v_and_b32_e32 v82, 0xffff, v81
	v_readlane_b32 s21, v255, 22
	s_nop 1
	v_cndmask_b32_e64 v81, v81, v82, s[20:21]
	v_readlane_b32 s20, v255, 19
	v_mfma_f32_32x32x16_bf16 v[32:47], v[120:123], v[152:155], v[32:47]
	v_and_b32_e32 v82, 0xffff0000, v134
	v_readlane_b32 s21, v255, 20
	s_nop 1
	v_cndmask_b32_e64 v82, v134, v82, s[20:21]
	v_readlane_b32 s20, v255, 17
	v_and_b32_e32 v83, 0xffff, v82
	v_mfma_f32_32x32x16_bf16 v[32:47], v[116:119], v[148:151], v[32:47]
	v_readlane_b32 s21, v255, 18
	s_nop 1
	v_cndmask_b32_e64 v82, v82, v83, s[20:21]
	v_readlane_b32 s20, v255, 15
	v_and_b32_e32 v83, 0xffff0000, v135
	v_readlane_b32 s21, v255, 16
	v_mfma_f32_32x32x16_bf16 v[32:47], v[112:115], v[144:147], v[32:47]
	s_nop 0
	v_cndmask_b32_e64 v83, v135, v83, s[20:21]
	v_readlane_b32 s20, v255, 13
	v_and_b32_e32 v84, 0xffff, v83
	v_readlane_b32 s21, v255, 14
	v_mfma_f32_32x32x16_bf16 v[32:47], v[108:111], v[140:143], v[32:47]
	s_nop 0
	v_cndmask_b32_e64 v83, v83, v84, s[20:21]
	v_readlane_b32 s20, v255, 33
	v_readlane_b32 s21, v255, 34
	v_or_b32_e32 v84, s14, v180
	v_mfma_f32_32x32x16_bf16 v[32:47], v[104:107], v[136:139], v[32:47]
	v_mfma_f32_32x32x16_bf16 v[48:63], v[72:75], v[80:83], v[48:63]
	s_waitcnt vmcnt(0)
	v_and_b32_e32 v72, 0xffff0000, v128
	v_cndmask_b32_e64 v72, v128, v72, s[10:11]
	v_and_b32_e32 v73, 0xffff, v72
	v_cndmask_b32_e64 v72, v72, v73, s[8:9]
	v_and_b32_e32 v73, 0xffff0000, v129
	v_cndmask_b32_e64 v73, v129, v73, s[6:7]
	v_and_b32_e32 v74, 0xffff, v73
	v_mfma_f32_32x32x16_bf16 v[32:47], v[76:79], v[80:83], v[32:47]
	v_cndmask_b32_e64 v73, v73, v74, s[40:41]
	v_and_b32_e32 v74, 0xffff0000, v130
	v_cndmask_b32_e64 v74, v130, v74, s[2:3]
	v_and_b32_e32 v75, 0xffff, v74
	v_cndmask_b32_e64 v74, v74, v75, s[20:21]
	v_readlane_b32 s20, v255, 31
	v_and_b32_e32 v75, 0xffff0000, v131
	v_readlane_b32 s21, v255, 32
	v_mov_b32_e32 v81, s15
	v_or_b32_e32 v80, s14, v182
	v_cndmask_b32_e64 v75, v131, v75, s[20:21]
	v_readlane_b32 s20, v255, 29
	v_and_b32_e32 v76, 0xffff, v75
	v_readlane_b32 s21, v255, 30
	s_nop 1
	v_cndmask_b32_e64 v75, v75, v76, s[20:21]
	s_nop 1
	v_mfma_f32_32x32x16_bf16 v[48:63], v[64:67], v[72:75], v[48:63]
	v_mov_b32_e32 v67, s15
	v_or_b32_e32 v66, s14, v188
	v_mov_b32_e32 v65, s15
	v_or_b32_e32 v64, s14, v190
	v_mfma_f32_32x32x16_bf16 v[32:47], v[68:71], v[72:75], v[32:47]
	ds_write_b128 v175, v[16:19]
	ds_write_b128 v175, v[20:23] offset:16
	ds_write_b128 v175, v[24:27] offset:32
	ds_write_b128 v175, v[28:31] offset:48
	ds_write_b128 v175, v[0:3] offset:128
	ds_write_b128 v175, v[4:7] offset:144
	ds_write_b128 v175, v[8:11] offset:160
	ds_write_b128 v175, v[12:15] offset:176
	ds_write_b128 v177, v[48:51]
	ds_write_b128 v177, v[52:55] offset:16
	ds_write_b128 v177, v[56:59] offset:32
	ds_write_b128 v177, v[60:63] offset:48
	ds_write_b128 v177, v[32:35] offset:128
	ds_write_b128 v177, v[36:39] offset:144
	ds_write_b128 v177, v[40:43] offset:160
	ds_write_b128 v177, v[44:47] offset:176
	v_lshlrev_b64 v[0:1], 11, v[92:93]
	v_lshl_add_u64 v[2:3], v[206:207], 0, v[0:1]
	v_lshl_add_u64 v[0:1], v[204:205], 0, v[0:1]
	global_load_dwordx4 v[60:63], v[2:3], off nt
	global_load_dwordx4 v[56:59], v[0:1], off nt
	global_load_dword v94, v179, s[12:13] offset:256
	v_lshlrev_b64 v[0:1], 11, v[88:89]
	v_lshl_add_u64 v[2:3], v[206:207], 0, v[0:1]
	v_lshl_add_u64 v[0:1], v[204:205], 0, v[0:1]
	global_load_dwordx4 v[52:55], v[2:3], off nt
	global_load_dwordx4 v[48:51], v[0:1], off nt
	global_load_dword v90, v179, s[12:13] offset:288
	v_lshlrev_b64 v[0:1], 11, v[84:85]
	v_lshl_add_u64 v[2:3], v[206:207], 0, v[0:1]
	v_lshl_add_u64 v[0:1], v[204:205], 0, v[0:1]
	global_load_dwordx4 v[44:47], v[2:3], off nt
	global_load_dwordx4 v[40:43], v[0:1], off nt
	global_load_dword v86, v179, s[12:13] offset:320
	v_lshlrev_b64 v[0:1], 11, v[80:81]
	v_lshl_add_u64 v[2:3], v[206:207], 0, v[0:1]
	v_lshl_add_u64 v[0:1], v[204:205], 0, v[0:1]
	v_mov_b32_e32 v75, s15
	v_or_b32_e32 v74, s14, v184
	global_load_dwordx4 v[36:39], v[2:3], off nt
	global_load_dwordx4 v[32:35], v[0:1], off nt
	global_load_dword v82, v179, s[12:13] offset:352
	v_lshlrev_b64 v[0:1], 11, v[74:75]
	v_lshl_add_u64 v[2:3], v[206:207], 0, v[0:1]
	v_lshl_add_u64 v[0:1], v[204:205], 0, v[0:1]
	v_mov_b32_e32 v71, s15
	v_or_b32_e32 v70, s14, v186
	global_load_dwordx4 v[24:27], v[2:3], off nt
	global_load_dwordx4 v[20:23], v[0:1], off nt
	global_load_dword v76, v179, s[12:13] offset:384
	v_lshlrev_b64 v[0:1], 11, v[70:71]
	v_lshl_add_u64 v[2:3], v[206:207], 0, v[0:1]
	v_lshl_add_u64 v[0:1], v[204:205], 0, v[0:1]
	global_load_dwordx4 v[16:19], v[2:3], off nt
	global_load_dwordx4 v[12:15], v[0:1], off nt
	global_load_dword v72, v179, s[12:13] offset:416
	v_lshlrev_b64 v[0:1], 11, v[66:67]
	v_lshlrev_b64 v[28:29], 11, v[64:65]
	v_lshl_add_u64 v[2:3], v[206:207], 0, v[0:1]
	v_lshl_add_u64 v[0:1], v[204:205], 0, v[0:1]
	v_lshl_add_u64 v[8:9], v[206:207], 0, v[28:29]
	v_lshl_add_u64 v[28:29], v[204:205], 0, v[28:29]
	global_load_dwordx4 v[4:7], v[2:3], off nt
	s_nop 0
	global_load_dwordx4 v[0:3], v[0:1], off nt
	s_nop 0
	global_load_dword v68, v179, s[12:13] offset:448
	s_nop 0
	global_load_dwordx4 v[8:11], v[8:9], off nt
	s_nop 0
	global_load_dwordx4 v[28:31], v[28:29], off nt
	s_nop 0
	global_load_dword v78, v179, s[12:13] offset:480
	s_waitcnt vmcnt(1)
	ds_read_b128 v[96:99], v173
	ds_read_b128 v[100:103], v173 offset:16
	v_lshlrev_b32_e32 v104, 16, v60
	v_and_b32_e32 v105, 0xffff0000, v60
	v_lshlrev_b32_e32 v60, 16, v61
	s_waitcnt lgkmcnt(1)
	v_pk_add_f32 v[96:97], v[94:95], v[96:97] op_sel_hi:[0,1]
	v_pk_mul_f32 v[96:97], v[96:97], v[104:105]
	v_lshlrev_b32_e32 v104, 16, v56
	v_and_b32_e32 v105, 0xffff0000, v56
	v_pk_mul_f32 v[96:97], v[96:97], v[104:105]
	v_and_b32_e32 v61, 0xffff0000, v61
	v_cvt_pk_bf16_f32 v56, v96, v97
	v_pk_add_f32 v[96:97], v[94:95], v[98:99] op_sel_hi:[0,1]
	v_pk_mul_f32 v[60:61], v[96:97], v[60:61]
	v_lshlrev_b32_e32 v96, 16, v57
	v_and_b32_e32 v97, 0xffff0000, v57
	v_pk_mul_f32 v[60:61], v[60:61], v[96:97]
	s_waitcnt lgkmcnt(0)
	v_pk_add_f32 v[96:97], v[94:95], v[100:101] op_sel_hi:[0,1]
	v_cvt_pk_bf16_f32 v57, v60, v61
	v_lshlrev_b32_e32 v60, 16, v62
	v_and_b32_e32 v61, 0xffff0000, v62
	v_pk_mul_f32 v[60:61], v[96:97], v[60:61]
	v_lshlrev_b32_e32 v96, 16, v58
	v_and_b32_e32 v97, 0xffff0000, v58
	v_pk_mul_f32 v[60:61], v[60:61], v[96:97]
	s_nop 0
	v_cvt_pk_bf16_f32 v58, v60, v61
	v_lshlrev_b32_e32 v60, 16, v63
	v_and_b32_e32 v61, 0xffff0000, v63
	v_pk_add_f32 v[62:63], v[94:95], v[102:103] op_sel_hi:[0,1]
	v_pk_mul_f32 v[60:61], v[62:63], v[60:61]
	v_lshlrev_b32_e32 v62, 16, v59
	v_and_b32_e32 v63, 0xffff0000, v59
	v_pk_mul_f32 v[60:61], v[60:61], v[62:63]
	s_nop 0
	v_cvt_pk_bf16_f32 v59, v60, v61
	v_lshlrev_b64 v[60:61], 12, v[92:93]
	v_lshl_add_u64 v[60:61], v[202:203], 0, v[60:61]
	global_store_dwordx4 v[60:61], v[56:59], off
	ds_read_b128 v[56:59], v173 offset:2176
	ds_read_b128 v[60:63], v173 offset:2192
	v_lshlrev_b32_e32 v92, 16, v52
	v_and_b32_e32 v93, 0xffff0000, v52
	v_lshlrev_b32_e32 v52, 16, v53
	s_waitcnt lgkmcnt(1)
	v_pk_add_f32 v[56:57], v[90:91], v[56:57] op_sel_hi:[0,1]
	v_pk_mul_f32 v[56:57], v[56:57], v[92:93]
	v_lshlrev_b32_e32 v92, 16, v48
	v_and_b32_e32 v93, 0xffff0000, v48
	v_pk_mul_f32 v[56:57], v[56:57], v[92:93]
	v_and_b32_e32 v53, 0xffff0000, v53
	v_cvt_pk_bf16_f32 v48, v56, v57
	v_pk_add_f32 v[56:57], v[90:91], v[58:59] op_sel_hi:[0,1]
	v_pk_mul_f32 v[52:53], v[56:57], v[52:53]
	v_lshlrev_b32_e32 v56, 16, v49
	v_and_b32_e32 v57, 0xffff0000, v49
	v_pk_mul_f32 v[52:53], v[52:53], v[56:57]
	s_waitcnt lgkmcnt(0)
	v_pk_add_f32 v[56:57], v[90:91], v[60:61] op_sel_hi:[0,1]
	v_cvt_pk_bf16_f32 v49, v52, v53
	v_lshlrev_b32_e32 v52, 16, v54
	v_and_b32_e32 v53, 0xffff0000, v54
	v_pk_mul_f32 v[52:53], v[56:57], v[52:53]
	v_lshlrev_b32_e32 v56, 16, v50
	v_and_b32_e32 v57, 0xffff0000, v50
	v_pk_mul_f32 v[52:53], v[52:53], v[56:57]
	v_lshlrev_b32_e32 v56, 16, v44
	v_cvt_pk_bf16_f32 v50, v52, v53
	v_lshlrev_b32_e32 v52, 16, v55
	v_and_b32_e32 v53, 0xffff0000, v55
	v_pk_add_f32 v[54:55], v[90:91], v[62:63] op_sel_hi:[0,1]
	v_pk_mul_f32 v[52:53], v[54:55], v[52:53]
	v_lshlrev_b32_e32 v54, 16, v51
	v_and_b32_e32 v55, 0xffff0000, v51
	v_pk_mul_f32 v[52:53], v[52:53], v[54:55]
	v_and_b32_e32 v57, 0xffff0000, v44
	v_cvt_pk_bf16_f32 v51, v52, v53
	v_lshlrev_b64 v[52:53], 12, v[88:89]
	v_lshl_add_u64 v[52:53], v[202:203], 0, v[52:53]
	global_store_dwordx4 v[52:53], v[48:51], off
	ds_read_b128 v[48:51], v173 offset:4352
	ds_read_b128 v[52:55], v173 offset:4368
	v_lshlrev_b32_e32 v44, 16, v45
	v_and_b32_e32 v45, 0xffff0000, v45
	s_waitcnt lgkmcnt(1)
	v_pk_add_f32 v[48:49], v[86:87], v[48:49] op_sel_hi:[0,1]
	v_pk_mul_f32 v[48:49], v[48:49], v[56:57]
	v_lshlrev_b32_e32 v56, 16, v40
	v_and_b32_e32 v57, 0xffff0000, v40
	v_pk_mul_f32 v[48:49], v[48:49], v[56:57]
	s_nop 0
	v_cvt_pk_bf16_f32 v40, v48, v49
	v_pk_add_f32 v[48:49], v[86:87], v[50:51] op_sel_hi:[0,1]
	v_pk_mul_f32 v[44:45], v[48:49], v[44:45]
	v_lshlrev_b32_e32 v48, 16, v41
	v_and_b32_e32 v49, 0xffff0000, v41
	v_pk_mul_f32 v[44:45], v[44:45], v[48:49]
	s_waitcnt lgkmcnt(0)
	v_pk_add_f32 v[48:49], v[86:87], v[52:53] op_sel_hi:[0,1]
	v_cvt_pk_bf16_f32 v41, v44, v45
	v_lshlrev_b32_e32 v44, 16, v46
	v_and_b32_e32 v45, 0xffff0000, v46
	v_pk_mul_f32 v[44:45], v[48:49], v[44:45]
	v_lshlrev_b32_e32 v48, 16, v42
	v_and_b32_e32 v49, 0xffff0000, v42
	v_pk_mul_f32 v[44:45], v[44:45], v[48:49]
	v_lshlrev_b32_e32 v48, 16, v36
	v_cvt_pk_bf16_f32 v42, v44, v45
	v_lshlrev_b32_e32 v44, 16, v47
	v_and_b32_e32 v45, 0xffff0000, v47
	v_pk_add_f32 v[46:47], v[86:87], v[54:55] op_sel_hi:[0,1]
	v_pk_mul_f32 v[44:45], v[46:47], v[44:45]
	v_lshlrev_b32_e32 v46, 16, v43
	v_and_b32_e32 v47, 0xffff0000, v43
	v_pk_mul_f32 v[44:45], v[44:45], v[46:47]
	v_and_b32_e32 v49, 0xffff0000, v36
	v_cvt_pk_bf16_f32 v43, v44, v45
	v_lshlrev_b64 v[44:45], 12, v[84:85]
	v_lshl_add_u64 v[44:45], v[202:203], 0, v[44:45]
	global_store_dwordx4 v[44:45], v[40:43], off
	ds_read_b128 v[40:43], v173 offset:6528
	ds_read_b128 v[44:47], v173 offset:6544
	v_lshlrev_b32_e32 v36, 16, v37
	v_and_b32_e32 v37, 0xffff0000, v37
	s_waitcnt lgkmcnt(1)
	v_pk_add_f32 v[40:41], v[82:83], v[40:41] op_sel_hi:[0,1]
	v_pk_mul_f32 v[40:41], v[40:41], v[48:49]
	v_lshlrev_b32_e32 v48, 16, v32
	v_and_b32_e32 v49, 0xffff0000, v32
	v_pk_mul_f32 v[40:41], v[40:41], v[48:49]
	s_nop 0
	v_cvt_pk_bf16_f32 v32, v40, v41
	v_pk_add_f32 v[40:41], v[82:83], v[42:43] op_sel_hi:[0,1]
	v_pk_mul_f32 v[36:37], v[40:41], v[36:37]
	v_lshlrev_b32_e32 v40, 16, v33
	v_and_b32_e32 v41, 0xffff0000, v33
	v_pk_mul_f32 v[36:37], v[36:37], v[40:41]
	s_waitcnt lgkmcnt(0)
	v_pk_add_f32 v[40:41], v[82:83], v[44:45] op_sel_hi:[0,1]
	v_cvt_pk_bf16_f32 v33, v36, v37
	v_lshlrev_b32_e32 v36, 16, v38
	v_and_b32_e32 v37, 0xffff0000, v38
	v_pk_mul_f32 v[36:37], v[40:41], v[36:37]
	v_lshlrev_b32_e32 v40, 16, v34
	v_and_b32_e32 v41, 0xffff0000, v34
	v_pk_mul_f32 v[36:37], v[36:37], v[40:41]
	v_lshlrev_b32_e32 v40, 16, v24
	v_cvt_pk_bf16_f32 v34, v36, v37
	v_lshlrev_b32_e32 v36, 16, v39
	v_and_b32_e32 v37, 0xffff0000, v39
	v_pk_add_f32 v[38:39], v[82:83], v[46:47] op_sel_hi:[0,1]
	v_pk_mul_f32 v[36:37], v[38:39], v[36:37]
	v_lshlrev_b32_e32 v38, 16, v35
	v_and_b32_e32 v39, 0xffff0000, v35
	v_pk_mul_f32 v[36:37], v[36:37], v[38:39]
	v_and_b32_e32 v41, 0xffff0000, v24
	v_cvt_pk_bf16_f32 v35, v36, v37
	v_lshlrev_b64 v[36:37], 12, v[80:81]
	v_lshl_add_u64 v[36:37], v[202:203], 0, v[36:37]
	global_store_dwordx4 v[36:37], v[32:35], off
	ds_read_b128 v[36:39], v173 offset:8704
	ds_read_b128 v[32:35], v173 offset:8720
	v_lshlrev_b32_e32 v24, 16, v25
	v_and_b32_e32 v25, 0xffff0000, v25
	s_waitcnt lgkmcnt(1)
	v_pk_add_f32 v[36:37], v[76:77], v[36:37] op_sel_hi:[0,1]
	v_pk_mul_f32 v[36:37], v[36:37], v[40:41]
	v_lshlrev_b32_e32 v40, 16, v20
	v_and_b32_e32 v41, 0xffff0000, v20
	v_pk_mul_f32 v[36:37], v[36:37], v[40:41]
	s_waitcnt lgkmcnt(0)
	v_pk_add_f32 v[32:33], v[76:77], v[32:33] op_sel_hi:[0,1]
	v_cvt_pk_bf16_f32 v20, v36, v37
	v_pk_add_f32 v[36:37], v[76:77], v[38:39] op_sel_hi:[0,1]
	v_pk_mul_f32 v[24:25], v[36:37], v[24:25]
	v_lshlrev_b32_e32 v36, 16, v21
	v_and_b32_e32 v37, 0xffff0000, v21
	v_pk_mul_f32 v[24:25], v[24:25], v[36:37]
	s_nop 0
	v_cvt_pk_bf16_f32 v21, v24, v25
	v_lshlrev_b32_e32 v24, 16, v26
	v_and_b32_e32 v25, 0xffff0000, v26
	v_pk_mul_f32 v[24:25], v[32:33], v[24:25]
	v_lshlrev_b32_e32 v32, 16, v22
	v_and_b32_e32 v33, 0xffff0000, v22
	v_pk_mul_f32 v[24:25], v[24:25], v[32:33]
	v_lshlrev_b32_e32 v32, 16, v16
	v_cvt_pk_bf16_f32 v22, v24, v25
	v_lshlrev_b32_e32 v24, 16, v27
	v_and_b32_e32 v25, 0xffff0000, v27
	v_pk_add_f32 v[26:27], v[76:77], v[34:35] op_sel_hi:[0,1]
	v_pk_mul_f32 v[24:25], v[26:27], v[24:25]
	v_lshlrev_b32_e32 v26, 16, v23
	v_and_b32_e32 v27, 0xffff0000, v23
	v_pk_mul_f32 v[24:25], v[24:25], v[26:27]
	v_and_b32_e32 v33, 0xffff0000, v16
	v_cvt_pk_bf16_f32 v23, v24, v25
	v_lshlrev_b64 v[24:25], 12, v[74:75]
	v_lshl_add_u64 v[24:25], v[202:203], 0, v[24:25]
	global_store_dwordx4 v[24:25], v[20:23], off
	ds_read_b128 v[20:23], v173 offset:10880
	ds_read_b128 v[24:27], v173 offset:10896
	v_lshlrev_b32_e32 v16, 16, v17
	v_and_b32_e32 v17, 0xffff0000, v17
	s_waitcnt lgkmcnt(1)
	v_pk_add_f32 v[20:21], v[72:73], v[20:21] op_sel_hi:[0,1]
	v_pk_mul_f32 v[20:21], v[20:21], v[32:33]
	v_lshlrev_b32_e32 v32, 16, v12
	v_and_b32_e32 v33, 0xffff0000, v12
	v_pk_mul_f32 v[20:21], v[20:21], v[32:33]
	s_nop 0
	v_cvt_pk_bf16_f32 v12, v20, v21
	v_pk_add_f32 v[20:21], v[72:73], v[22:23] op_sel_hi:[0,1]
	v_pk_mul_f32 v[16:17], v[20:21], v[16:17]
	v_lshlrev_b32_e32 v20, 16, v13
	v_and_b32_e32 v21, 0xffff0000, v13
	v_pk_mul_f32 v[16:17], v[16:17], v[20:21]
	s_waitcnt lgkmcnt(0)
	v_pk_add_f32 v[20:21], v[72:73], v[24:25] op_sel_hi:[0,1]
	v_cvt_pk_bf16_f32 v13, v16, v17
	v_lshlrev_b32_e32 v16, 16, v18
	v_and_b32_e32 v17, 0xffff0000, v18
	v_pk_mul_f32 v[16:17], v[20:21], v[16:17]
	v_lshlrev_b32_e32 v20, 16, v14
	v_and_b32_e32 v21, 0xffff0000, v14
	v_pk_mul_f32 v[16:17], v[16:17], v[20:21]
	v_lshlrev_b32_e32 v20, 16, v4
	v_cvt_pk_bf16_f32 v14, v16, v17
	v_lshlrev_b32_e32 v16, 16, v19
	v_and_b32_e32 v17, 0xffff0000, v19
	v_pk_add_f32 v[18:19], v[72:73], v[26:27] op_sel_hi:[0,1]
	v_pk_mul_f32 v[16:17], v[18:19], v[16:17]
	v_lshlrev_b32_e32 v18, 16, v15
	v_and_b32_e32 v19, 0xffff0000, v15
	v_pk_mul_f32 v[16:17], v[16:17], v[18:19]
	v_and_b32_e32 v21, 0xffff0000, v4
	v_cvt_pk_bf16_f32 v15, v16, v17
	v_lshlrev_b64 v[16:17], 12, v[70:71]
	v_lshl_add_u64 v[16:17], v[202:203], 0, v[16:17]
	global_store_dwordx4 v[16:17], v[12:15], off
	ds_read_b128 v[12:15], v173 offset:13056
	ds_read_b128 v[16:19], v173 offset:13072
	v_lshlrev_b32_e32 v4, 16, v5
	v_and_b32_e32 v5, 0xffff0000, v5
	s_waitcnt lgkmcnt(1)
	v_pk_add_f32 v[12:13], v[68:69], v[12:13] op_sel_hi:[0,1]
	v_pk_mul_f32 v[12:13], v[12:13], v[20:21]
	v_lshlrev_b32_e32 v20, 16, v0
	v_and_b32_e32 v21, 0xffff0000, v0
	v_pk_mul_f32 v[12:13], v[12:13], v[20:21]
	s_nop 0
	v_cvt_pk_bf16_f32 v0, v12, v13
	v_pk_add_f32 v[12:13], v[68:69], v[14:15] op_sel_hi:[0,1]
	v_pk_mul_f32 v[4:5], v[12:13], v[4:5]
	v_lshlrev_b32_e32 v12, 16, v1
	v_and_b32_e32 v13, 0xffff0000, v1
	v_pk_mul_f32 v[4:5], v[4:5], v[12:13]
	s_waitcnt lgkmcnt(0)
	v_pk_add_f32 v[12:13], v[68:69], v[16:17] op_sel_hi:[0,1]
	v_cvt_pk_bf16_f32 v1, v4, v5
	v_lshlrev_b32_e32 v4, 16, v6
	v_and_b32_e32 v5, 0xffff0000, v6
	v_pk_mul_f32 v[4:5], v[12:13], v[4:5]
	v_lshlrev_b32_e32 v12, 16, v2
	v_and_b32_e32 v13, 0xffff0000, v2
	v_pk_mul_f32 v[4:5], v[4:5], v[12:13]
	v_lshlrev_b32_e32 v12, 16, v8
	v_cvt_pk_bf16_f32 v2, v4, v5
	v_lshlrev_b32_e32 v4, 16, v7
	v_and_b32_e32 v5, 0xffff0000, v7
	v_pk_add_f32 v[6:7], v[68:69], v[18:19] op_sel_hi:[0,1]
	v_pk_mul_f32 v[4:5], v[6:7], v[4:5]
	v_lshlrev_b32_e32 v6, 16, v3
	v_and_b32_e32 v7, 0xffff0000, v3
	v_pk_mul_f32 v[4:5], v[4:5], v[6:7]
	v_and_b32_e32 v13, 0xffff0000, v8
	v_cvt_pk_bf16_f32 v3, v4, v5
	v_lshlrev_b64 v[4:5], 12, v[66:67]
	v_lshl_add_u64 v[4:5], v[202:203], 0, v[4:5]
	global_store_dwordx4 v[4:5], v[0:3], off
	ds_read_b128 v[0:3], v173 offset:15232
	ds_read_b128 v[4:7], v173 offset:15248
	v_lshlrev_b32_e32 v8, 16, v9
	v_and_b32_e32 v9, 0xffff0000, v9
	s_waitcnt vmcnt(7) lgkmcnt(1)
	v_pk_add_f32 v[0:1], v[78:79], v[0:1] op_sel_hi:[0,1]
	v_pk_add_f32 v[2:3], v[78:79], v[2:3] op_sel_hi:[0,1]
	v_pk_mul_f32 v[0:1], v[0:1], v[12:13]
	v_lshlrev_b32_e32 v12, 16, v28
	v_and_b32_e32 v13, 0xffff0000, v28
	v_pk_mul_f32 v[2:3], v[2:3], v[8:9]
	v_lshlrev_b32_e32 v8, 16, v29
	v_and_b32_e32 v9, 0xffff0000, v29
	v_pk_mul_f32 v[0:1], v[0:1], v[12:13]
	v_pk_mul_f32 v[2:3], v[2:3], v[8:9]
	v_cvt_pk_bf16_f32 v0, v0, v1
	v_cvt_pk_bf16_f32 v1, v2, v3
	v_lshlrev_b32_e32 v2, 16, v10
	v_and_b32_e32 v3, 0xffff0000, v10
	s_waitcnt lgkmcnt(0)
	v_pk_add_f32 v[4:5], v[78:79], v[4:5] op_sel_hi:[0,1]
	v_pk_mul_f32 v[2:3], v[4:5], v[2:3]
	v_lshlrev_b32_e32 v4, 16, v30
	v_and_b32_e32 v5, 0xffff0000, v30
	v_pk_mul_f32 v[2:3], v[2:3], v[4:5]
	v_lshlrev_b32_e32 v4, 16, v11
	v_and_b32_e32 v5, 0xffff0000, v11
	v_pk_add_f32 v[6:7], v[78:79], v[6:7] op_sel_hi:[0,1]
	v_pk_mul_f32 v[4:5], v[6:7], v[4:5]
	v_lshlrev_b32_e32 v6, 16, v31
	v_and_b32_e32 v7, 0xffff0000, v31
	v_pk_mul_f32 v[4:5], v[4:5], v[6:7]
	v_cvt_pk_bf16_f32 v2, v2, v3
	v_cvt_pk_bf16_f32 v3, v4, v5
	v_lshlrev_b64 v[4:5], 12, v[64:65]
	v_lshl_add_u64 v[4:5], v[202:203], 0, v[4:5]
	global_store_dwordx4 v[4:5], v[0:3], off
	s_cbranch_scc1 .LBB0_124
	v_readlane_b32 s44, v253, 42
	v_readlane_b32 s29, v253, 41
	v_readlane_b32 s45, v253, 43
	v_readlane_b32 s37, v253, 46
	s_mov_b32 s46, s27
